# hand gather loops + PRO gain hoist + S1 twiddle hoist + de-serialized G3/WO epilogues + first seam uses XCD barrier instead of cg grid.sync
# speedup vs baseline: 1.0327x; 1.0215x over previous
.LBB0_85:
	s_and_b64 vcc, exec, s[14:15]
	s_cbranch_vccnz .LBB0_84
	s_lshl_b32 s28, s16, 25
	s_lshl_b64 s[42:43], s[28:29], 2
	s_add_u32 s84, s62, s42
	s_addc_u32 s85, s63, s43
	s_add_u32 s17, s64, s42
	s_addc_u32 s28, s65, s43
	s_sub_u32 s42, s17, s84
	s_subb_u32 s43, s28, s85
	s_ashr_i64 s[42:43], s[42:43], 2
	s_and_b64 s[44:45], s[34:35], exec
	s_brev_b32 s17, 16
	s_cselect_b32 s17, s17, 0x10000000
	s_add_u32 s86, s54, s17
	s_addc_u32 s87, s55, 0
	s_lshl_b32 s28, s16, 15
	s_lshl_b64 s[44:45], s[28:29], 2
	s_add_u32 s88, s74, s44
	s_addc_u32 s89, s75, s45
	s_lshl_b32 s28, s16, 11
	s_lshl_b64 s[16:17], s[28:29], 2
	s_add_u32 s16, s40, s16
	s_addc_u32 s17, s41, s17
	s_and_b64 s[44:45], s[30:31], exec
	s_cselect_b32 s45, 0, s43
	s_cselect_b32 s44, 0, s42
	s_lshl_b64 s[44:45], s[44:45], 2
	s_add_u32 s28, s84, s44
	s_addc_u32 s39, s85, s45
	s_add_u32 s28, s28, s79
	s_addc_u32 s39, s39, 0
	s_add_u32 s44, s28, s80
	s_addc_u32 s45, s39, 0
	s_waitcnt vmcnt(18)
	v_lshl_add_u64 v[14:15], s[44:45], 0, v[72:73]
	s_and_b64 s[44:45], s[26:27], exec
	s_cselect_b32 s45, 0, s43
	s_cselect_b32 s44, 0, s42
	s_lshl_b64 s[44:45], s[44:45], 2
	s_add_u32 s28, s84, s44
	s_addc_u32 s39, s85, s45
	s_add_u32 s28, s28, s81
	s_addc_u32 s39, s39, 0
	s_add_u32 s44, s28, s82
	s_addc_u32 s45, s39, 0
	global_load_dwordx4 v[2:5], v[14:15], off offset:3072
	global_load_dwordx4 v[6:9], v[14:15], off offset:2048
	global_load_dwordx4 v[10:13], v[14:15], off offset:1024
	global_load_dwordx4 v[46:49], v[14:15], off
	v_lshl_add_u64 v[14:15], s[44:45], 0, v[72:73]
	global_load_dwordx4 v[50:53], v[14:15], off offset:3072
	global_load_dwordx4 v[54:57], v[14:15], off offset:2048
	global_load_dwordx4 v[58:61], v[14:15], off offset:1024
	global_load_dwordx4 v[62:65], v[14:15], off
	v_lshl_add_u64 v[14:15], s[16:17], 0, v[72:73]
	s_add_u32 s16, s16, s38
	s_mov_b32 s39, s29
	s_addc_u32 s17, s17, 0
	v_lshl_add_u64 v[80:81], v[14:15], 0, s[38:39]
	v_lshl_add_u64 v[82:83], s[16:17], 0, v[72:73]
	global_load_dwordx4 v[140:143], v[80:81], off
	global_load_dwordx4 v[144:147], v[82:83], off offset:1024
	global_load_dwordx4 v[148:151], v[82:83], off offset:2048
	global_load_dwordx4 v[152:155], v[82:83], off offset:3072
	v_readlane_b32 s28, v248, 3
	s_branch .LBB0_88

.LBB0_88:
	s_add_i32 s39, s0, s28
	s_add_i32 s16, s78, s28
	s_add_i32 s44, s76, s28
	s_cmp_lt_i32 s16, 0x10000
	s_cselect_b32 s45, s16, s39
	s_ashr_i32 s46, s45, 1
	s_cmpk_gt_i32 s46, 0x3fff
	s_cselect_b32 s17, s43, 0
	s_cselect_b32 s16, s42, 0
	s_lshl_b64 s[16:17], s[16:17], 2
	s_add_u32 s16, s84, s16
	s_addc_u32 s17, s85, s17
	s_lshl_b32 s46, s46, 13
	s_and_b32 s46, s46, 0x7ffe000
	s_add_u32 s16, s16, s46
	s_addc_u32 s17, s17, 0
	s_lshl_b32 s45, s45, 12
	s_and_b32 s45, s45, 0x1000
	s_add_u32 s16, s16, s45
	s_addc_u32 s17, s17, 0
	s_cmp_lt_i32 s44, 0x10000
	s_cselect_b32 s44, s44, s39
	s_ashr_i32 s45, s44, 1
	s_cmpk_gt_i32 s45, 0x3fff
	s_waitcnt vmcnt(14)
	v_lshl_add_u64 v[26:27], s[16:17], 0, v[72:73]
	s_cselect_b32 s17, s43, 0
	s_cselect_b32 s16, s42, 0
	s_lshl_b64 s[16:17], s[16:17], 2
	s_add_u32 s16, s84, s16
	s_addc_u32 s17, s85, s17
	s_lshl_b32 s45, s45, 13
	s_and_b32 s45, s45, 0x7ffe000
	s_add_u32 s16, s16, s45
	s_addc_u32 s17, s17, 0
	s_lshl_b32 s44, s44, 12
	s_and_b32 s44, s44, 0x1000
	s_add_u32 s16, s16, s44
	s_addc_u32 s17, s17, 0
	v_lshl_add_u64 v[42:43], s[16:17], 0, v[72:73]
	global_load_dwordx4 v[14:17], v[26:27], off
	global_load_dwordx4 v[18:21], v[26:27], off offset:1024
	global_load_dwordx4 v[22:25], v[26:27], off offset:2048
	s_nop 0
	global_load_dwordx4 v[26:29], v[26:27], off offset:3072
	s_nop 0
	global_load_dwordx4 v[30:33], v[42:43], off
	global_load_dwordx4 v[34:37], v[42:43], off offset:1024
	global_load_dwordx4 v[38:41], v[42:43], off offset:2048
	s_nop 0
	global_load_dwordx4 v[42:45], v[42:43], off offset:3072
	s_ashr_i32 s16, s39, 1
	s_cmpk_lt_i32 s16, 0x4000
	s_cselect_b64 s[46:47], -1, 0
	s_cmpk_gt_i32 s16, 0x3fff
	s_cselect_b64 s[44:45], -1, 0
	s_and_b64 vcc, exec, s[44:45]
	s_cbranch_vccnz .LBB0_92
	s_waitcnt vmcnt(8)
	v_pk_mul_f32 v[64:65], v[64:65], v[142:143]
	v_pk_mul_f32 v[62:63], v[62:63], v[140:141]
	v_cndmask_b32_e64 v84, 0, 1, s[46:47]
	v_cmp_ne_u32_e64 s[16:17], 1, v84
	s_andn2_b64 vcc, exec, s[46:47]
	s_cbranch_vccz .LBB0_93

.LBB0_91:
	s_waitcnt vmcnt(8)
	v_pk_mul_f32 v[56:57], v[56:57], v[150:151]
	v_pk_mul_f32 v[54:55], v[54:55], v[148:149]
	s_and_b64 vcc, exec, s[16:17]
	s_mov_b64 s[16:17], 0x10000
	s_cbranch_vccz .LBB0_95
	s_branch .LBB0_96

.LBB0_93:
	s_waitcnt vmcnt(8)
	v_pk_mul_f32 v[60:61], v[60:61], v[146:147]
	v_pk_mul_f32 v[58:59], v[58:59], v[144:145]
	s_and_b64 vcc, exec, s[16:17]
	s_cbranch_vccz .LBB0_91

.LBB0_95:
	s_mov_b64 s[16:17], 0
	s_waitcnt vmcnt(8)
	v_pk_mul_f32 v[52:53], v[52:53], v[154:155]
	v_pk_mul_f32 v[50:51], v[50:51], v[152:153]

.LBB0_111:
	s_ashr_i32 s16, s39, 1
	s_cmpk_lt_i32 s16, 0x4000
	s_cselect_b64 s[46:47], -1, 0
	s_cmpk_gt_i32 s16, 0x3fff
	s_cselect_b64 s[44:45], -1, 0
	s_and_b64 vcc, exec, s[44:45]
	s_cbranch_vccnz .LBB0_115
	v_pk_mul_f32 v[48:49], v[48:49], v[142:143]
	v_pk_mul_f32 v[46:47], v[46:47], v[140:141]
	v_cndmask_b32_e64 v50, 0, 1, s[46:47]
	v_cmp_ne_u32_e64 s[16:17], 1, v50
	s_andn2_b64 vcc, exec, s[46:47]
	s_cbranch_vccz .LBB0_116

.LBB0_114:
	v_pk_mul_f32 v[8:9], v[8:9], v[150:151]
	v_pk_mul_f32 v[6:7], v[6:7], v[148:149]
	s_and_b64 vcc, exec, s[16:17]
	s_mov_b64 s[16:17], 0x10000
	s_cbranch_vccz .LBB0_118
	s_branch .LBB0_119

.LBB0_116:
	v_pk_mul_f32 v[12:13], v[12:13], v[146:147]
	v_pk_mul_f32 v[10:11], v[10:11], v[144:145]
	s_and_b64 vcc, exec, s[16:17]
	s_cbranch_vccz .LBB0_114

.LBB0_118:
	s_mov_b64 s[16:17], 0
	v_pk_mul_f32 v[4:5], v[4:5], v[154:155]
	v_pk_mul_f32 v[2:3], v[2:3], v[152:153]

.LBB0_137:
	s_cmp_gt_i32 s57, 1
	s_cselect_b64 s[4:5], -1, 0
	s_and_b64 s[0:1], s[22:23], s[4:5]
	s_andn2_b64 vcc, exec, s[0:1]
	s_cbranch_vccnz .LBB0_149
	s_waitcnt vmcnt(0)
	s_waitcnt vmcnt(0) lgkmcnt(0)
	s_barrier
	s_mov_b64 s[6:7], exec
	v_readlane_b32 s0, v248, 1
	v_readlane_b32 s1, v248, 2
	s_and_b64 s[0:1], s[6:7], s[0:1]
	s_mov_b64 exec, s[0:1]
	s_cbranch_execz .Lxb0_228
	s_add_i32 s0, 0, 0x20020
	v_mov_b32_e32 v0, s0
	s_waitcnt vmcnt(0) expcnt(0) lgkmcnt(0)
	ds_read_b32 v2, v0
	s_add_i32 s0, 0, 0x20024
	v_mov_b32_e32 v0, s0
	ds_read_b32 v0, v0
	s_waitcnt lgkmcnt(1)
	v_cmp_ne_u32_e32 vcc, 0, v2
	s_cbranch_vccnz .Lxb0_192
	s_add_u32 s8, s54, 0x4200
	s_addc_u32 s9, s55, 0
	s_add_u32 s10, s54, 0x4400
	s_addc_u32 s11, s55, 0
	s_add_u32 s12, s54, 0x4500
	s_addc_u32 s13, s55, 0
	s_add_u32 s14, s54, 0x4600
	s_addc_u32 s15, s55, 0
	s_add_u32 s16, s54, 0x4700
	s_addc_u32 s17, s55, 0
	s_add_u32 s20, s54, 0x4800
	s_addc_u32 s21, s55, 0
	s_add_u32 s22, s54, 0x4900
	s_addc_u32 s23, s55, 0
	s_add_u32 s24, s54, 0x4a00
	s_addc_u32 s25, s55, 0
	s_add_u32 s26, s54, 0x4b00
	s_addc_u32 s27, s55, 0
	s_add_u32 s28, s54, 0x4c00
	s_addc_u32 s29, s55, 0
	s_add_u32 s30, s54, 0x4d00
	s_addc_u32 s31, s55, 0
	s_add_u32 s34, s54, 0x4e00
	s_addc_u32 s35, s55, 0
	s_add_u32 s42, s54, 0x4f00
	s_addc_u32 s43, s55, 0
	s_add_u32 s44, s54, 0x5000
	s_addc_u32 s45, s55, 0
	s_add_u32 s46, s54, 0x5100
	s_addc_u32 s47, s55, 0
	s_add_u32 s50, s54, 0x5200
	s_addc_u32 s51, s55, 0
	s_mul_i32 s0, s59, s87
	s_add_u32 s60, s54, 0x5300
	s_mul_i32 s0, s0, s58
	s_addc_u32 s61, s55, 0
	s_mov_b32 s1, 1
	v_mov_b32_e32 v16, 0
	s_branch .Lxb0_180

.Lxb0_228:
	s_or_b64 exec, exec, s[6:7]
	s_waitcnt lgkmcnt(0)
	s_barrier
.LBB0_149:
	s_cmp_lt_i32 s56, 2
	s_cselect_b64 s[10:11], -1, 0
	s_and_b64 s[0:1], s[10:11], s[4:5]
	s_add_u32 s38, s54, 0x1c000000
	s_addc_u32 s39, s55, 0
	s_ashr_i32 s3, s2, 31
	s_lshr_b32 s4, s3, 29
	s_add_i32 s4, s2, s4
	s_ashr_i32 s92, s4, 3
	s_and_b32 s4, s4, -8
	s_sub_i32 s85, s2, s4
	s_cmp_lt_i32 s85, 0
	v_lshrrev_b32_e32 v0, 1, v197
	s_cselect_b64 s[4:5], -1, 0
	v_writelane_b32 v248, s4, 5
	s_andn2_b64 vcc, exec, s[0:1]
	v_and_b32_e32 v203, 24, v0
	v_writelane_b32 v248, s5, 6
	s_cbranch_vccnz .LBB0_175
	s_cmpk_gt_i32 s2, 0x3ff
	s_movk_i32 s4, 0x100
	v_readfirstlane_b32 s7, v197
	v_mbcnt_lo_u32_b32 v0, -1, 0
	v_mbcnt_hi_u32_b32 v0, -1, v0
	s_cbranch_scc1 .LBB0_175
	v_lshrrev_b32_e32 v0, 5, v197
	v_and_b32_e32 v0, 4, v0
	v_bfe_u32 v1, v197, 2, 2
	v_or3_b32 v0, v0, v1, v203
	v_lshlrev_b32_e32 v1, 4, v197
	v_add_u32_e32 v2, 0x2000, v1
	v_lshrrev_b32_e32 v2, 7, v2
	s_waitcnt vmcnt(29)
	v_and_b32_e32 v4, 32, v197
	s_movk_i32 s16, 0xe0
	s_waitcnt vmcnt(21)
	v_bitop3_b32 v12, v1, v4, 48 bitop3:0x6c
	s_waitcnt vmcnt(20)
	v_and_b32_e32 v13, 64, v197
	s_waitcnt vmcnt(19)
	v_and_b32_e32 v14, 0xf0, v2
	s_waitcnt vmcnt(18)
	v_bfe_u32 v15, v197, 2, 4
	v_and_or_b32 v3, v2, s16, v0
	v_or_b32_e32 v1, v12, v13
	v_or_b32_e32 v2, v14, v15
	s_lshr_b32 s8, s7, 6
	s_ashr_i32 s5, s4, 31
	v_lshrrev_b32_e32 v1, 1, v1
	v_mul_lo_u32 v2, s4, v2
	s_lshr_b32 s9, s7, 8
	s_lshl_b64 s[12:13], s[4:5], 8
	s_lshl_b64 s[14:15], s[4:5], 9
	s_lshl_b32 s0, s8, 10
	s_lshl_b32 s6, s85, 7
	v_add_lshl_u32 v130, v2, v1, 1
	v_lshrrev_b32_e32 v2, 3, v197
	s_movk_i32 s16, 0x60
	s_add_u32 s1, s54, 0x100000
	v_and_or_b32 v0, v2, s16, v0
	v_readlane_b32 s16, v248, 5
	s_addc_u32 s34, s55, 0
	v_readlane_b32 s17, v248, 6
	s_mul_i32 s20, s85, 0x81
	s_and_b64 s[16:17], s[16:17], exec
	s_cselect_b32 s6, s20, s6
	s_add_i32 s6, s6, s92
	s_ashr_i32 s16, s6, 31
	s_lshr_b32 s16, s16, 20
	s_add_i32 s16, s6, s16
	s_ashr_i32 s17, s16, 12
	s_lshl_b32 s20, s17, 3
	s_sub_i32 s17, 2, s20
	v_mul_lo_u32 v3, s4, v3
	s_min_u32 s21, s17, 8
	s_and_b32 s16, s16, 0xfffff000
	v_add_lshl_u32 v128, v3, v1, 1
	s_sub_i32 s22, s6, s16
	v_cvt_f32_ubyte0_e32 v3, s21
	s_waitcnt vmcnt(17)
	v_and_b32_e32 v16, 0x70, v2
	v_cvt_f32_i32_e32 v2, s22
	v_rcp_iflag_f32_e32 v4, v3
	v_mul_lo_u32 v0, s4, v0
	v_add_lshl_u32 v132, v0, v1, 1
	v_or_b32_e32 v0, v16, v15
	v_mul_lo_u32 v0, s4, v0
	v_add_lshl_u32 v134, v0, v1, 1
	v_mul_f32_e32 v0, v2, v4
	v_trunc_f32_e32 v0, v0
	v_fma_f32 v1, -v0, v3, v2
	v_cvt_i32_f32_e32 v0, v0
	s_ashr_i32 s6, s22, 30
	s_or_b32 s6, s6, 1
	v_cmp_ge_f32_e64 s[16:17], |v1|, v3
	s_and_b64 s[16:17], s[16:17], exec
	s_cselect_b32 s6, s6, 0
	v_readfirstlane_b32 s16, v0
	s_add_i32 s6, s16, s6
	s_mul_i32 s16, s6, s21
	s_sub_i32 s16, s22, s16
	s_sext_i32_i16 s16, s16
	s_add_i32 s70, s20, s16
	s_ashr_i32 s16, s70, 31
	s_mul_i32 s16, s14, s16
	s_mul_hi_u32 s17, s14, s70
	s_add_i32 s20, s17, s16
	s_lshr_b64 s[16:17], s[4:5], 23
	s_mul_i32 s17, s16, s70
	s_add_i32 s17, s20, s17
	s_bfe_i64 s[20:21], s[6:7], 0x100000
	s_mul_i32 s21, s14, s21
	s_mul_hi_u32 s23, s14, s20
	s_add_i32 s21, s23, s21
	s_mul_i32 s16, s16, s20
	s_add_i32 s21, s21, s16
	s_mul_i32 s16, s14, s20
	s_add_u32 s30, s68, s16
	s_addc_u32 s31, s69, s21
	s_add_i32 s35, s0, 0
	s_add_i32 m0, s35, 0x10000
	s_mul_i32 s22, s14, s70
	global_load_lds_dwordx4 v132, s[30:31]
	s_add_i32 m0, s35, 0x12000
	s_add_u32 s20, s30, s12
	global_load_lds_dwordx4 v128, s[30:31]
	s_addc_u32 s21, s31, s13
	s_add_i32 m0, s35, 0x14000
	v_mov_b32_e32 v137, 0
	global_load_lds_dwordx4 v132, s[20:21]
	s_add_i32 m0, s35, 0x16000
	s_add_u32 s28, s1, s22
	s_addc_u32 s29, s34, s17
	s_add_i32 s40, s35, 0x2000
	global_load_lds_dwordx4 v128, s[20:21]
	s_mov_b32 m0, s35
	s_add_u32 s16, s28, s12
	global_load_lds_dwordx4 v134, s[28:29]
	s_mov_b32 m0, s40
	s_addc_u32 s17, s29, s13
	s_add_i32 s41, s35, 0x4000
	global_load_lds_dwordx4 v130, s[28:29]
	s_mov_b32 m0, s41
	s_add_i32 s42, s35, 0x6000
	global_load_lds_dwordx4 v134, s[16:17]
	s_mov_b32 m0, s42
	v_mov_b32_e32 v133, v137
	global_load_lds_dwordx4 v130, s[16:17]
	v_mov_b32_e32 v129, v137
	v_mov_b32_e32 v135, v137
	v_mov_b32_e32 v131, v137
	s_cmp_eq_u32 s9, 1
	s_mov_b32 s17, 0
	v_lshl_add_u64 v[10:11], s[30:31], 0, v[132:133]
	v_lshl_add_u64 v[6:7], s[30:31], 0, v[128:129]
	v_lshl_add_u64 v[2:3], s[20:21], 0, v[132:133]
	v_lshl_add_u64 v[0:1], s[20:21], 0, v[128:129]
	v_lshl_add_u64 v[8:9], s[28:29], 0, v[134:135]
	v_lshl_add_u64 v[4:5], s[28:29], 0, v[130:131]
	s_cselect_b64 s[20:21], -1, 0
	s_cmp_lg_u32 s9, 1
	s_movk_i32 s43, 0x4000
	s_cbranch_scc1 .LBB0_153
	s_barrier

.LBB0_229:
	s_cmp_lt_i32 s56, 3
	s_cselect_b64 s[0:1], -1, 0
	s_and_b64 s[4:5], s[0:1], s[4:5]
	s_andn2_b64 vcc, exec, s[4:5]
	s_cbranch_vccnz .LBB0_237
	s_andn2_b64 vcc, exec, s[18:19]
	v_mbcnt_lo_u32_b32 v0, -1, 0
	v_mbcnt_hi_u32_b32 v0, -1, v0
	s_cbranch_vccnz .LBB0_237
	s_add_u32 s6, s54, 0x4100000
	v_readlane_b32 s12, v248, 3
	s_addc_u32 s7, s55, 0
	s_lshl_b32 s8, s12, 7
	s_and_b32 s0, s8, 0x80
	v_lshlrev_b32_e32 v106, 1, v0
	v_add_u32_e32 v0, s0, v106
	s_ashr_i32 s0, s33, 5
	s_and_b32 s0, s0, -16
	s_ashr_i32 s1, s0, 31
	s_lshl_b64 s[0:1], s[0:1], 18
	s_add_u32 s0, s38, s0
	s_addc_u32 s1, s39, s1
	s_lshl_b32 s9, s33, 9
	s_and_b32 s9, s9, 0x3fc00
	s_add_u32 s0, s0, s9
	s_addc_u32 s1, s1, 0
	v_ashrrev_i32_e32 v1, 31, v0
	v_lshl_add_u64 v[0:1], v[0:1], 1, s[0:1]
	s_mov_b32 s0, 0x40000
	v_add_co_u32_e32 v2, vcc, s0, v0
	s_mov_b32 s1, 0x80000
	s_waitcnt vmcnt(0)
	v_addc_co_u32_e32 v3, vcc, 0, v1, vcc
	v_add_co_u32_e32 v4, vcc, s1, v0
	s_mov_b32 s9, 0xc0000
	s_nop 0
	v_addc_co_u32_e32 v5, vcc, 0, v1, vcc
	v_add_co_u32_e32 v6, vcc, s9, v0
	s_mov_b32 s11, 0x100000
	s_nop 0
	v_addc_co_u32_e32 v7, vcc, 0, v1, vcc
	global_load_dword v15, v[0:1], off
	global_load_dword v12, v[0:1], off offset:512
	global_load_dword v13, v[2:3], off
	global_load_dword v10, v[2:3], off offset:512
	global_load_dword v11, v[4:5], off
	global_load_dword v8, v[4:5], off offset:512
	global_load_dword v9, v[6:7], off
	global_load_dword v17, v[6:7], off offset:512
	v_add_co_u32_e32 v2, vcc, s11, v0
	s_mov_b32 s13, 0x140000
	s_nop 0
	v_addc_co_u32_e32 v3, vcc, 0, v1, vcc
	v_add_co_u32_e32 v4, vcc, s13, v0
	s_mov_b32 s15, 0x180000
	s_nop 0
	v_addc_co_u32_e32 v5, vcc, 0, v1, vcc
	v_add_co_u32_e32 v18, vcc, s15, v0
	s_mov_b32 s17, 0x1c0000
	s_nop 0
	v_addc_co_u32_e32 v19, vcc, 0, v1, vcc
	v_add_co_u32_e32 v20, vcc, s17, v0
	s_mov_b32 s19, 0x200000
	s_nop 0
	v_addc_co_u32_e32 v21, vcc, 0, v1, vcc
	global_load_dword v25, v[2:3], off
	global_load_dword v27, v[2:3], off offset:512
	global_load_dword v29, v[4:5], off
	global_load_dword v28, v[4:5], off offset:512
	global_load_dword v7, v[18:19], off
	global_load_dword v6, v[18:19], off offset:512
	s_nop 0
	global_load_dword v5, v[20:21], off
	global_load_dword v4, v[20:21], off offset:512
	v_add_co_u32_e32 v2, vcc, s19, v0
	s_mov_b32 s21, 0x240000
	s_nop 0
	v_addc_co_u32_e32 v3, vcc, 0, v1, vcc
	v_add_co_u32_e32 v18, vcc, s21, v0
	s_mov_b32 s23, 0x280000
	s_nop 0
	v_addc_co_u32_e32 v19, vcc, 0, v1, vcc
	v_add_co_u32_e32 v20, vcc, s23, v0
	s_mov_b32 s28, 0x2c0000
	s_nop 0
	v_addc_co_u32_e32 v21, vcc, 0, v1, vcc
	v_add_co_u32_e32 v22, vcc, s28, v0
	s_mov_b32 s29, 0x300000
	s_nop 0
	v_addc_co_u32_e32 v23, vcc, 0, v1, vcc
	global_load_dword v40, v[2:3], off
	global_load_dword v37, v[2:3], off offset:512
	global_load_dword v35, v[18:19], off
	global_load_dword v34, v[18:19], off offset:512
	global_load_dword v33, v[20:21], off
	global_load_dword v32, v[20:21], off offset:512
	global_load_dword v31, v[22:23], off
	global_load_dword v30, v[22:23], off offset:512
	v_add_co_u32_e32 v2, vcc, s29, v0
	s_mov_b32 s30, 0x340000
	s_nop 0
	v_addc_co_u32_e32 v3, vcc, 0, v1, vcc
	v_add_co_u32_e32 v18, vcc, s30, v0
	s_mov_b32 s31, 0x380000
	s_nop 0
	v_addc_co_u32_e32 v19, vcc, 0, v1, vcc
	v_add_co_u32_e32 v20, vcc, s31, v0
	s_mov_b32 s34, 0x3c0000
	s_nop 0
	v_addc_co_u32_e32 v21, vcc, 0, v1, vcc
	v_add_co_u32_e32 v0, vcc, s34, v0
	s_lshl_b32 s10, s2, 11
	s_nop 0
	v_addc_co_u32_e32 v1, vcc, 0, v1, vcc
	global_load_dword v45, v[2:3], off
	global_load_dword v44, v[2:3], off offset:512
	global_load_dword v43, v[18:19], off
	global_load_dword v42, v[18:19], off offset:512
	global_load_dword v41, v[20:21], off
	global_load_dword v39, v[20:21], off offset:512
	global_load_dword v38, v[0:1], off
	global_load_dword v36, v[0:1], off offset:512
	s_lshl_b32 s12, s12, 8
	s_add_i32 s63, s10, s12
	s_lshl_b32 s10, s2, 10
	s_lshl_b32 s35, s58, 11
	s_add_i32 s40, s10, s8
	s_lshl_b32 s41, s58, 10
	s_movk_i32 s42, 0x4000
	s_mov_b32 s43, 0xffff0000
	s_mov_b32 s8, 0x3f6c835e
	s_mov_b32 s10, 0x3ec3ef16
	s_mov_b32 s12, 0x3f3504f3
	s_mov_b32 s14, 0x3ec3ef15
	s_mov_b32 s16, 0xb33bbd2e
	s_mov_b32 s18, 0xbf3504f3
	s_mov_b32 s20, 0xbec3ef15
	s_mov_b32 s22, 0xbf6c835e
	s_movk_i32 s44, 0x7fff
	s_movk_i32 s45, 0x2000
	s_movk_i32 s46, 0x6000
	s_movk_i32 s47, 0x1000
	s_movk_i32 s50, 0x3000
	s_movk_i32 s51, 0x5000
	s_movk_i32 s60, 0x7000
	s_mov_b32 s64, s33
	v_readlane_b32 s96, v248, 3
	s_nop 0
	s_lshl_b32 s96, s96, 7
	s_and_b32 s96, s96, 0x80
	v_add_u32_e32 v240, s96, v106
	v_lshlrev_b32_e32 v240, 3, v240
	s_add_u32 s78, s6, 0x1000
	s_addc_u32 s79, s7, 0
	s_add_u32 s80, s6, 0x3000
	s_addc_u32 s81, s7, 0
	s_add_u32 s82, s6, 0x5000
	s_addc_u32 s83, s7, 0
	s_add_u32 s94, s6, 0x7000
	s_addc_u32 s95, s7, 0
	global_load_dwordx4 v[168:171], v240, s[78:79] offset:-4096
	global_load_dwordx4 v[172:175], v240, s[78:79] offset:-2048
	global_load_dwordx4 v[176:179], v240, s[78:79] offset:0
	global_load_dwordx4 v[180:183], v240, s[78:79] offset:2048
	global_load_dwordx4 v[184:187], v240, s[80:81] offset:-4096
	global_load_dwordx4 v[188:191], v240, s[80:81] offset:-2048
	global_load_dwordx4 v[192:195], v240, s[80:81] offset:0
	global_load_dwordx4 v[204:207], v240, s[80:81] offset:2048
	global_load_dwordx4 v[208:211], v240, s[82:83] offset:-4096
	global_load_dwordx4 v[212:215], v240, s[82:83] offset:-2048
	global_load_dwordx4 v[216:219], v240, s[82:83] offset:0
	global_load_dwordx4 v[220:223], v240, s[82:83] offset:2048
	global_load_dwordx4 v[224:227], v240, s[94:95] offset:-4096
	global_load_dwordx4 v[228:231], v240, s[94:95] offset:-2048
	global_load_dwordx4 v[232:235], v240, s[94:95] offset:0
	global_load_dwordx4 v[236:239], v240, s[94:95] offset:2048
	s_waitcnt vmcnt(0)
	s_branch .LBB0_233
.LBB0_232:
	v_lshl_add_u64 v[0:1], v[2:3], 3, s[6:7]
	v_mov_b32_e32 v140, v168
	v_mov_b32_e32 v141, v169
	v_mov_b32_e32 v142, v170
	v_mov_b32_e32 v143, v171
	v_lshlrev_b32_e32 v22, 16, v12
	v_and_b32_e32 v23, 0xffff0000, v12
	v_lshlrev_b32_e32 v20, 16, v10
	v_and_b32_e32 v21, 0xffff0000, v10
	v_lshlrev_b32_e32 v18, 16, v8
	v_and_b32_e32 v19, 0xffff0000, v8
	v_lshlrev_b32_e32 v16, 16, v17
	v_and_b32_e32 v17, 0xffff0000, v17
	v_lshlrev_b32_e32 v26, 16, v27
	v_and_b32_e32 v27, 0xffff0000, v27
	v_lshlrev_b32_e32 v62, 16, v28
	v_and_b32_e32 v63, 0xffff0000, v28
	v_lshlrev_b32_e32 v66, 16, v6
	v_and_b32_e32 v67, 0xffff0000, v6
	v_lshlrev_b32_e32 v70, 16, v4
	v_and_b32_e32 v71, 0xffff0000, v4
	v_lshlrev_b32_e32 v88, 16, v37
	v_and_b32_e32 v89, 0xffff0000, v37
	v_lshlrev_b32_e32 v86, 16, v34
	v_and_b32_e32 v87, 0xffff0000, v34
	v_lshlrev_b32_e32 v84, 16, v32
	v_and_b32_e32 v85, 0xffff0000, v32
	v_lshlrev_b32_e32 v82, 16, v30
	v_and_b32_e32 v83, 0xffff0000, v30
	v_lshlrev_b32_e32 v104, 16, v44
	v_and_b32_e32 v105, 0xffff0000, v44
	v_lshlrev_b32_e32 v102, 16, v42
	v_and_b32_e32 v103, 0xffff0000, v42
	v_lshlrev_b32_e32 v100, 16, v39
	v_and_b32_e32 v101, 0xffff0000, v39
	v_lshlrev_b32_e32 v98, 16, v36
	v_and_b32_e32 v99, 0xffff0000, v36
	v_lshlrev_b32_e32 v14, 16, v15
	v_and_b32_e32 v15, 0xffff0000, v15
	v_lshlrev_b32_e32 v12, 16, v13
	v_and_b32_e32 v13, 0xffff0000, v13
	v_lshlrev_b32_e32 v10, 16, v11
	v_and_b32_e32 v11, 0xffff0000, v11
	v_lshlrev_b32_e32 v8, 16, v9
	v_and_b32_e32 v9, 0xffff0000, v9
	v_lshlrev_b32_e32 v24, 16, v25
	v_and_b32_e32 v25, 0xffff0000, v25
	v_lshlrev_b32_e32 v60, 16, v29
	v_and_b32_e32 v61, 0xffff0000, v29
	v_lshlrev_b32_e32 v64, 16, v7
	v_and_b32_e32 v65, 0xffff0000, v7
	v_lshlrev_b32_e32 v68, 16, v5
	v_and_b32_e32 v69, 0xffff0000, v5
	v_lshlrev_b32_e32 v80, 16, v40
	v_and_b32_e32 v81, 0xffff0000, v40
	v_lshlrev_b32_e32 v78, 16, v35
	v_and_b32_e32 v79, 0xffff0000, v35
	v_lshlrev_b32_e32 v76, 16, v33
	v_and_b32_e32 v77, 0xffff0000, v33
	v_lshlrev_b32_e32 v74, 16, v31
	v_and_b32_e32 v75, 0xffff0000, v31
	v_lshlrev_b32_e32 v96, 16, v45
	v_and_b32_e32 v97, 0xffff0000, v45
	v_lshlrev_b32_e32 v94, 16, v43
	v_and_b32_e32 v95, 0xffff0000, v43
	v_lshlrev_b32_e32 v92, 16, v41
	v_and_b32_e32 v93, 0xffff0000, v41
	v_lshlrev_b32_e32 v90, 16, v38
	v_and_b32_e32 v91, 0xffff0000, v38
	v_pk_add_f32 v[30:31], v[22:23], v[88:89]
	v_pk_add_f32 v[34:35], v[26:27], v[104:105]
	v_pk_add_f32 v[38:39], v[20:21], v[86:87]
	v_pk_add_f32 v[42:43], v[62:63], v[102:103]
	v_pk_add_f32 v[46:47], v[18:19], v[84:85]
	v_pk_add_f32 v[50:51], v[66:67], v[100:101]
	v_pk_add_f32 v[54:55], v[16:17], v[82:83]
	v_pk_add_f32 v[58:59], v[70:71], v[98:99]
	s_ashr_i32 s26, s64, 5
	v_pk_add_f32 v[28:29], v[14:15], v[80:81]
	v_pk_add_f32 v[32:33], v[24:25], v[96:97]
	v_pk_add_f32 v[144:145], v[30:31], v[34:35]
	v_pk_add_f32 v[36:37], v[12:13], v[78:79]
	v_pk_add_f32 v[40:41], v[60:61], v[94:95]
	v_pk_add_f32 v[148:149], v[38:39], v[42:43]
	v_pk_add_f32 v[44:45], v[10:11], v[76:77]
	v_pk_add_f32 v[48:49], v[64:65], v[92:93]
	v_pk_add_f32 v[152:153], v[46:47], v[50:51]
	v_pk_add_f32 v[52:53], v[8:9], v[74:75]
	v_pk_add_f32 v[56:57], v[68:69], v[90:91]
	v_pk_add_f32 v[156:157], v[54:55], v[58:59]
	s_and_b32 s64, s26, -16
	v_pk_add_f32 v[6:7], v[28:29], v[32:33]
	v_pk_add_f32 v[146:147], v[36:37], v[40:41]
	v_pk_add_f32 v[150:151], v[44:45], v[48:49]
	v_pk_add_f32 v[154:155], v[52:53], v[56:57]
	v_pk_add_f32 v[160:161], v[144:145], v[152:153]
	v_pk_add_f32 v[164:165], v[148:149], v[156:157]
	s_ashr_i32 s65, s64, 31
	v_pk_add_f32 v[158:159], v[6:7], v[150:151]
	v_pk_add_f32 v[162:163], v[146:147], v[154:155]
	v_pk_add_f32 v[72:73], v[160:161], v[164:165]
	v_mov_b32_e32 v167, v142
	v_mov_b32_e32 v142, v141
	s_and_b32 s26, s63, 0x1fe00
	s_lshl_b64 s[64:65], s[64:65], 18
	v_pk_add_f32 v[4:5], v[158:159], v[162:163]
	v_mov_b32_e32 v166, v140
	v_pk_mul_f32 v[140:141], v[142:143], v[72:73]
	s_add_u32 s27, s38, s64
	v_pk_fma_f32 v[140:141], v[166:167], v[4:5], v[140:141]
	v_pk_mul_f32 v[4:5], v[142:143], v[4:5]
	s_addc_u32 s63, s39, s65
	s_lshl_b32 s26, s26, 1
	v_pk_fma_f32 v[4:5], v[166:167], v[72:73], v[4:5] neg_lo:[0,0,1] neg_hi:[0,0,1]
	v_bfe_u32 v72, v140, 16, 1
	s_add_u32 s26, s27, s26
	v_add3_u32 v72, v140, v72, s44
	v_bfe_u32 v73, v141, 16, 1
	s_addc_u32 s27, s63, 0
	v_lshrrev_b32_e32 v72, 16, v72
	v_add3_u32 v73, v141, v73, s44
	v_lshl_add_u64 v[0:1], v[2:3], 1, s[26:27]
	v_and_or_b32 v72, v73, s43, v72
	global_store_dword v[0:1], v72, off
	v_bfe_u32 v72, v4, 16, 1
	v_add3_u32 v4, v4, v72, s44
	v_bfe_u32 v72, v5, 16, 1
	v_lshrrev_b32_e32 v4, 16, v4
	v_add3_u32 v5, v5, v72, s44
	v_and_or_b32 v4, v5, s43, v4
	v_lshl_add_u64 v[72:73], v[2:3], 3, s[6:7]
	global_store_dword v[0:1], v4, off offset:512
	v_add_co_u32_e32 v4, vcc, s50, v72
	v_pk_add_f32 v[150:151], v[6:7], v[150:151] neg_lo:[0,1] neg_hi:[0,1]
	s_nop 0
	v_addc_co_u32_e32 v5, vcc, 0, v73, vcc
	v_pk_add_f32 v[148:149], v[148:149], v[156:157] neg_lo:[0,1] neg_hi:[0,1]
	v_pk_add_f32 v[144:145], v[144:145], v[152:153] neg_lo:[0,1] neg_hi:[0,1]
	v_pk_add_f32 v[146:147], v[146:147], v[154:155] neg_lo:[0,1] neg_hi:[0,1]
	v_pk_add_f32 v[6:7], v[150:151], v[148:149]
	v_pk_add_f32 v[152:153], v[144:145], v[146:147] neg_lo:[0,1] neg_hi:[0,1]
	v_add_co_u32_e32 v2, vcc, s51, v72
	v_pk_add_f32 v[148:149], v[150:151], v[148:149] neg_lo:[0,1] neg_hi:[0,1]
	s_nop 0
	v_addc_co_u32_e32 v3, vcc, 0, v73, vcc
	v_add_co_u32_e32 v154, vcc, s11, v0
	v_pk_add_f32 v[144:145], v[144:145], v[146:147]
	s_nop 0
	v_addc_co_u32_e32 v155, vcc, 0, v1, vcc
	v_pk_add_f32 v[12:13], v[12:13], v[78:79] neg_lo:[0,1] neg_hi:[0,1]
	v_pk_add_f32 v[62:63], v[62:63], v[102:103] neg_lo:[0,1] neg_hi:[0,1]
	v_pk_add_f32 v[10:11], v[10:11], v[76:77] neg_lo:[0,1] neg_hi:[0,1]
	v_pk_add_f32 v[66:67], v[66:67], v[100:101] neg_lo:[0,1] neg_hi:[0,1]
	v_pk_add_f32 v[8:9], v[8:9], v[74:75] neg_lo:[0,1] neg_hi:[0,1]
	v_pk_add_f32 v[70:71], v[70:71], v[98:99] neg_lo:[0,1] neg_hi:[0,1]
	v_pk_add_f32 v[22:23], v[22:23], v[88:89] neg_lo:[0,1] neg_hi:[0,1]
	v_pk_add_f32 v[20:21], v[20:21], v[86:87] neg_lo:[0,1] neg_hi:[0,1]
	v_pk_add_f32 v[60:61], v[60:61], v[94:95] neg_lo:[0,1] neg_hi:[0,1]
	v_pk_add_f32 v[18:19], v[18:19], v[84:85] neg_lo:[0,1] neg_hi:[0,1]
	v_pk_add_f32 v[64:65], v[64:65], v[92:93] neg_lo:[0,1] neg_hi:[0,1]
	v_pk_add_f32 v[16:17], v[16:17], v[82:83] neg_lo:[0,1] neg_hi:[0,1]
	v_pk_add_f32 v[68:69], v[68:69], v[90:91] neg_lo:[0,1] neg_hi:[0,1]
	v_pk_add_f32 v[76:77], v[12:13], v[62:63]
	v_pk_add_f32 v[84:85], v[10:11], v[66:67]
	v_pk_add_f32 v[88:89], v[8:9], v[70:71]
	v_pk_add_f32 v[24:25], v[24:25], v[96:97] neg_lo:[0,1] neg_hi:[0,1]
	v_pk_add_f32 v[82:83], v[20:21], v[60:61] neg_lo:[0,1] neg_hi:[0,1]
	v_pk_add_f32 v[86:87], v[18:19], v[64:65] neg_lo:[0,1] neg_hi:[0,1]
	v_pk_add_f32 v[90:91], v[16:17], v[68:69] neg_lo:[0,1] neg_hi:[0,1]
	v_pk_mul_f32 v[92:93], v[76:77], s[8:9] op_sel_hi:[1,0]
	v_pk_mul_f32 v[76:77], v[76:77], s[10:11] op_sel_hi:[1,0]
	v_pk_mul_f32 v[84:85], v[84:85], s[12:13] op_sel_hi:[1,0]
	v_pk_mul_f32 v[94:95], v[88:89], s[14:15] op_sel_hi:[1,0]
	v_pk_mul_f32 v[88:89], v[88:89], s[8:9] op_sel_hi:[1,0]
	v_pk_add_f32 v[14:15], v[14:15], v[80:81] neg_lo:[0,1] neg_hi:[0,1]
	v_pk_add_f32 v[26:27], v[26:27], v[104:105] neg_lo:[0,1] neg_hi:[0,1]
	v_pk_add_f32 v[80:81], v[22:23], v[24:25] neg_lo:[0,1] neg_hi:[0,1]
	v_pk_fma_f32 v[92:93], v[82:83], s[10:11], v[92:93] op_sel_hi:[1,0,1]
	v_pk_fma_f32 v[82:83], v[82:83], s[8:9], v[76:77] op_sel_hi:[1,0,1] neg_lo:[0,0,1] neg_hi:[0,0,1]
	v_pk_fma_f32 v[96:97], v[86:87], s[12:13], v[84:85] op_sel_hi:[1,0,1]
	v_pk_fma_f32 v[84:85], v[86:87], s[12:13], v[84:85] op_sel_hi:[1,0,1] neg_lo:[0,0,1] neg_hi:[0,0,1]
	v_pk_fma_f32 v[88:89], v[90:91], s[14:15], v[88:89] op_sel_hi:[1,0,1] neg_lo:[0,0,1] neg_hi:[0,0,1]
	v_pk_add_f32 v[78:79], v[14:15], v[26:27]
	v_pk_fma_f32 v[86:87], v[90:91], s[8:9], v[94:95] op_sel_hi:[1,0,1]
	v_pk_add_f32 v[94:95], v[80:81], v[84:85]
	v_pk_add_f32 v[100:101], v[82:83], v[88:89]
	v_pk_add_f32 v[90:91], v[78:79], v[96:97]
	v_pk_add_f32 v[98:99], v[92:93], v[86:87]
	v_pk_add_f32 v[102:103], v[94:95], v[100:101]
	v_pk_add_f32 v[76:77], v[90:91], v[98:99]
	v_pk_add_f32 v[80:81], v[80:81], v[84:85] neg_lo:[0,1] neg_hi:[0,1]
	v_pk_add_f32 v[84:85], v[92:93], v[86:87] neg_lo:[0,1] neg_hi:[0,1]
	v_pk_add_f32 v[78:79], v[78:79], v[96:97] neg_lo:[0,1] neg_hi:[0,1]
	v_pk_add_f32 v[82:83], v[82:83], v[88:89] neg_lo:[0,1] neg_hi:[0,1]
	v_pk_add_f32 v[88:89], v[80:81], v[84:85] neg_lo:[0,1] neg_hi:[0,1]
	v_pk_add_f32 v[86:87], v[78:79], v[82:83]
	v_pk_add_f32 v[80:81], v[80:81], v[84:85]
	v_pk_add_f32 v[78:79], v[78:79], v[82:83] neg_lo:[0,1] neg_hi:[0,1]
	v_pk_add_f32 v[32:33], v[28:29], v[32:33] neg_lo:[0,1] neg_hi:[0,1]
	v_pk_add_f32 v[34:35], v[30:31], v[34:35] neg_lo:[0,1] neg_hi:[0,1]
	v_pk_add_f32 v[28:29], v[36:37], v[40:41] neg_lo:[0,1] neg_hi:[0,1]
	v_pk_add_f32 v[30:31], v[38:39], v[42:43] neg_lo:[0,1] neg_hi:[0,1]
	v_pk_add_f32 v[36:37], v[44:45], v[48:49] neg_lo:[0,1] neg_hi:[0,1]
	v_pk_add_f32 v[38:39], v[46:47], v[50:51] neg_lo:[0,1] neg_hi:[0,1]
	v_pk_add_f32 v[40:41], v[52:53], v[56:57] neg_lo:[0,1] neg_hi:[0,1]
	v_pk_add_f32 v[42:43], v[54:55], v[58:59] neg_lo:[0,1] neg_hi:[0,1]
	v_pk_mul_f32 v[28:29], v[28:29], s[12:13] op_sel_hi:[1,0]
	v_pk_fma_f32 v[44:45], v[36:37], s[16:17], v[38:39] op_sel_hi:[1,0,1]
	v_pk_fma_f32 v[36:37], v[38:39], s[16:17], v[36:37] op_sel_hi:[1,0,1] neg_lo:[0,0,1] neg_hi:[0,0,1]
	v_pk_mul_f32 v[38:39], v[40:41], s[12:13] op_sel_hi:[1,0]
	v_pk_fma_f32 v[46:47], v[30:31], s[12:13], v[28:29] op_sel_hi:[1,0,1] neg_lo:[0,0,1] neg_hi:[0,0,1]
	v_pk_fma_f32 v[48:49], v[42:43], s[12:13], v[38:39] op_sel_hi:[1,0,1] neg_lo:[0,0,1] neg_hi:[0,0,1]
	v_pk_fma_f32 v[38:39], v[42:43], s[18:19], v[38:39] op_sel_hi:[1,0,1] neg_lo:[0,0,1] neg_hi:[0,0,1]
	v_mov_b32_e32 v140, v184
	v_mov_b32_e32 v141, v185
	v_mov_b32_e32 v142, v186
	v_mov_b32_e32 v143, v187
	v_mov_b32_e32 v156, v140
	v_mov_b32_e32 v157, v142
	v_mov_b32_e32 v142, v141
	v_pk_mul_f32 v[140:141], v[156:157], v[6:7]
	v_pk_mul_f32 v[6:7], v[142:143], v[6:7]
	v_pk_fma_f32 v[140:141], v[142:143], v[152:153], v[140:141]
	v_pk_fma_f32 v[6:7], v[156:157], v[152:153], v[6:7] neg_lo:[0,0,1] neg_hi:[0,0,1]
	v_bfe_u32 v139, v140, 16, 1
	v_bfe_u32 v142, v141, 16, 1
	v_bfe_u32 v143, v6, 16, 1
	v_add3_u32 v139, v140, v139, s44
	v_bfe_u32 v152, v7, 16, 1
	v_add3_u32 v140, v141, v142, s44
	v_add3_u32 v6, v6, v143, s44
	v_lshrrev_b32_e32 v139, 16, v139
	v_add3_u32 v7, v7, v152, s44
	v_lshrrev_b32_e32 v6, 16, v6
	v_and_or_b32 v139, v140, s43, v139
	v_and_or_b32 v6, v7, s43, v6
	global_store_dword v[154:155], v139, off
	global_store_dword v[154:155], v6, off offset:512
	v_pk_add_f32 v[152:153], v[158:159], v[162:163] neg_lo:[0,1] neg_hi:[0,1]
	v_pk_add_f32 v[154:155], v[160:161], v[164:165] neg_lo:[0,1] neg_hi:[0,1]
	v_add_co_u32_e32 v6, vcc, s60, v72
	v_pk_fma_f32 v[40:41], v[30:31], s[12:13], v[28:29] op_sel_hi:[1,0,1]
	s_nop 0
	v_addc_co_u32_e32 v7, vcc, 0, v73, vcc
	v_add_co_u32_e32 v156, vcc, s19, v0
	v_pk_add_f32 v[50:51], v[34:35], v[36:37]
	s_nop 0
	v_addc_co_u32_e32 v157, vcc, 0, v1, vcc
	v_add_co_u32_e32 v146, vcc, s29, v0
	v_pk_add_f32 v[54:55], v[46:47], v[38:39]
	s_nop 0
	v_addc_co_u32_e32 v147, vcc, 0, v1, vcc
	v_add_co_u32_e32 v74, vcc, s45, v72
	v_pk_add_f32 v[42:43], v[32:33], v[44:45]
	s_nop 0
	v_addc_co_u32_e32 v75, vcc, 0, v73, vcc
	v_add_co_u32_e32 v104, vcc, s0, v0
	v_pk_add_f32 v[52:53], v[40:41], v[48:49]
	s_nop 0
	v_addc_co_u32_e32 v105, vcc, 0, v1, vcc
	v_pk_add_f32 v[30:31], v[50:51], v[54:55]
	v_pk_add_f32 v[28:29], v[42:43], v[52:53]
	v_pk_add_f32 v[34:35], v[34:35], v[36:37] neg_lo:[0,1] neg_hi:[0,1]
	v_pk_add_f32 v[36:37], v[40:41], v[48:49] neg_lo:[0,1] neg_hi:[0,1]
	v_pk_add_f32 v[32:33], v[32:33], v[44:45] neg_lo:[0,1] neg_hi:[0,1]
	v_pk_add_f32 v[38:39], v[46:47], v[38:39] neg_lo:[0,1] neg_hi:[0,1]
	v_pk_add_f32 v[44:45], v[34:35], v[36:37] neg_lo:[0,1] neg_hi:[0,1]
	v_pk_add_f32 v[40:41], v[32:33], v[38:39]
	v_pk_add_f32 v[32:33], v[32:33], v[38:39] neg_lo:[0,1] neg_hi:[0,1]
	v_pk_add_f32 v[34:35], v[34:35], v[36:37]
	v_pk_add_f32 v[12:13], v[12:13], v[62:63] neg_lo:[0,1] neg_hi:[0,1]
	v_pk_add_f32 v[10:11], v[10:11], v[66:67] neg_lo:[0,1] neg_hi:[0,1]
	v_pk_add_f32 v[8:9], v[8:9], v[70:71] neg_lo:[0,1] neg_hi:[0,1]
	v_pk_add_f32 v[14:15], v[14:15], v[26:27] neg_lo:[0,1] neg_hi:[0,1]
	v_pk_add_f32 v[22:23], v[22:23], v[24:25]
	v_pk_add_f32 v[20:21], v[20:21], v[60:61]
	v_pk_add_f32 v[18:19], v[18:19], v[64:65]
	v_pk_add_f32 v[16:17], v[16:17], v[68:69]
	v_pk_mul_f32 v[24:25], v[12:13], s[14:15] op_sel_hi:[1,0]
	v_pk_mul_f32 v[12:13], v[12:13], s[8:9] op_sel_hi:[1,0]
	v_pk_mul_f32 v[10:11], v[10:11], s[12:13] op_sel_hi:[1,0]
	v_pk_mul_f32 v[26:27], v[8:9], s[8:9] op_sel_hi:[1,0]
	v_pk_mul_f32 v[8:9], v[8:9], s[14:15] op_sel_hi:[1,0]
	v_pk_fma_f32 v[24:25], v[20:21], s[8:9], v[24:25] op_sel_hi:[1,0,1]
	v_pk_fma_f32 v[12:13], v[20:21], s[14:15], v[12:13] op_sel_hi:[1,0,1] neg_lo:[0,0,1] neg_hi:[0,0,1]
	v_pk_fma_f32 v[20:21], v[18:19], s[12:13], v[10:11] op_sel_hi:[1,0,1] neg_lo:[0,0,1] neg_hi:[0,0,1]
	v_pk_fma_f32 v[18:19], v[18:19], s[18:19], v[10:11] op_sel_hi:[1,0,1] neg_lo:[0,0,1] neg_hi:[0,0,1]
	v_pk_fma_f32 v[26:27], v[16:17], s[20:21], v[26:27] op_sel_hi:[1,0,1] neg_lo:[0,0,1] neg_hi:[0,0,1]
	v_pk_fma_f32 v[16:17], v[16:17], s[22:23], v[8:9] op_sel_hi:[1,0,1]
	s_mov_b32 s63, s62
	s_add_i32 s40, s40, s41
	s_mov_b32 s64, s61
	v_mov_b32_e32 v140, v208
	v_mov_b32_e32 v141, v209
	v_mov_b32_e32 v142, v210
	v_mov_b32_e32 v143, v211
	v_mov_b32_e32 v159, v142
	v_mov_b32_e32 v142, v141
	v_mov_b32_e32 v158, v140
	v_pk_mul_f32 v[140:141], v[142:143], v[154:155]
	v_pk_mul_f32 v[142:143], v[152:153], v[142:143]
	v_pk_fma_f32 v[140:141], v[152:153], v[158:159], v[140:141]
	v_pk_fma_f32 v[142:143], v[158:159], v[154:155], v[142:143] neg_lo:[0,0,1] neg_hi:[0,0,1]
	v_bfe_u32 v139, v140, 16, 1
	v_bfe_u32 v152, v141, 16, 1
	v_bfe_u32 v153, v142, 16, 1
	v_add3_u32 v139, v140, v139, s44
	v_bfe_u32 v154, v143, 16, 1
	v_add3_u32 v140, v141, v152, s44
	v_add3_u32 v141, v142, v153, s44
	v_lshrrev_b32_e32 v139, 16, v139
	v_add3_u32 v142, v143, v154, s44
	v_lshrrev_b32_e32 v141, 16, v141
	v_and_or_b32 v139, v140, s43, v139
	v_and_or_b32 v140, v142, s43, v141
	global_store_dword v[156:157], v139, off
	global_store_dword v[156:157], v140, off offset:512
	v_mov_b32_e32 v140, v224
	v_mov_b32_e32 v141, v225
	v_mov_b32_e32 v142, v226
	v_mov_b32_e32 v143, v227
	v_mov_b32_e32 v151, v142
	v_mov_b32_e32 v142, v141
	v_mov_b32_e32 v150, v140
	v_pk_mul_f32 v[140:141], v[144:145], v[142:143]
	v_pk_mul_f32 v[142:143], v[148:149], v[142:143]
	v_pk_fma_f32 v[140:141], v[148:149], v[150:151], v[140:141]
	v_pk_fma_f32 v[142:143], v[144:145], v[150:151], v[142:143] neg_lo:[0,0,1] neg_hi:[0,0,1]
	v_bfe_u32 v139, v140, 16, 1
	v_bfe_u32 v144, v141, 16, 1
	v_bfe_u32 v145, v142, 16, 1
	v_add3_u32 v139, v140, v139, s44
	v_bfe_u32 v148, v143, 16, 1
	v_add3_u32 v140, v141, v144, s44
	v_add3_u32 v141, v142, v145, s44
	v_lshrrev_b32_e32 v139, 16, v139
	v_add3_u32 v142, v143, v148, s44
	v_lshrrev_b32_e32 v141, 16, v141
	v_and_or_b32 v139, v140, s43, v139
	v_and_or_b32 v140, v142, s43, v141
	global_store_dword v[146:147], v139, off
	global_store_dword v[146:147], v140, off offset:512
	v_mov_b32_e32 v140, v172
	v_mov_b32_e32 v141, v173
	v_mov_b32_e32 v142, v174
	v_mov_b32_e32 v143, v175
	v_mov_b32_e32 v145, v142
	v_mov_b32_e32 v142, v141
	v_mov_b32_e32 v144, v140
	v_pk_mul_f32 v[140:141], v[102:103], v[142:143]
	v_pk_mul_f32 v[142:143], v[76:77], v[142:143]
	v_pk_fma_f32 v[76:77], v[76:77], v[144:145], v[140:141]
	v_pk_fma_f32 v[102:103], v[102:103], v[144:145], v[142:143] neg_lo:[0,0,1] neg_hi:[0,0,1]
	v_bfe_u32 v139, v76, 16, 1
	v_bfe_u32 v140, v77, 16, 1
	v_bfe_u32 v141, v102, 16, 1
	v_add3_u32 v76, v76, v139, s44
	v_bfe_u32 v142, v103, 16, 1
	v_add3_u32 v77, v77, v140, s44
	v_add3_u32 v102, v102, v141, s44
	v_lshrrev_b32_e32 v76, 16, v76
	v_add3_u32 v103, v103, v142, s44
	v_lshrrev_b32_e32 v102, 16, v102
	v_and_or_b32 v76, v77, s43, v76
	v_and_or_b32 v77, v103, s43, v102
	global_store_dword v[104:105], v76, off
	global_store_dword v[104:105], v77, off offset:512
	v_add_co_u32_e32 v102, vcc, s42, v72
	v_mov_b32_e32 v74, v188
	v_mov_b32_e32 v75, v189
	v_mov_b32_e32 v76, v190
	v_mov_b32_e32 v77, v191
	v_mov_b32_e32 v97, v76
	v_mov_b32_e32 v76, v75
	v_mov_b32_e32 v96, v74
	v_pk_mul_f32 v[74:75], v[88:89], v[76:77]
	v_pk_mul_f32 v[76:77], v[86:87], v[76:77]
	v_pk_fma_f32 v[74:75], v[86:87], v[96:97], v[74:75]
	v_pk_fma_f32 v[76:77], v[88:89], v[96:97], v[76:77] neg_lo:[0,0,1] neg_hi:[0,0,1]
	v_bfe_u32 v86, v74, 16, 1
	v_addc_co_u32_e32 v103, vcc, 0, v73, vcc
	v_bfe_u32 v87, v75, 16, 1
	v_bfe_u32 v88, v76, 16, 1
	v_add3_u32 v74, v74, v86, s44
	v_add_co_u32_e32 v92, vcc, s13, v0
	v_bfe_u32 v89, v77, 16, 1
	v_add3_u32 v75, v75, v87, s44
	v_add3_u32 v76, v76, v88, s44
	v_lshrrev_b32_e32 v74, 16, v74
	v_addc_co_u32_e32 v93, vcc, 0, v1, vcc
	v_add3_u32 v77, v77, v89, s44
	v_lshrrev_b32_e32 v76, 16, v76
	v_and_or_b32 v74, v75, s43, v74
	v_and_or_b32 v75, v77, s43, v76
	global_store_dword v[92:93], v74, off
	global_store_dword v[92:93], v75, off offset:512
	v_pk_add_f32 v[88:89], v[90:91], v[98:99] neg_lo:[0,1] neg_hi:[0,1]
	v_pk_add_f32 v[90:91], v[94:95], v[100:101] neg_lo:[0,1] neg_hi:[0,1]
	v_add_co_u32_e32 v86, vcc, s46, v72
	v_mov_b32_e32 v74, v212
	v_mov_b32_e32 v75, v213
	v_mov_b32_e32 v76, v214
	v_mov_b32_e32 v77, v215
	v_mov_b32_e32 v95, v76
	v_mov_b32_e32 v76, v75
	v_mov_b32_e32 v94, v74
	v_pk_mul_f32 v[74:75], v[90:91], v[76:77]
	v_pk_mul_f32 v[76:77], v[88:89], v[76:77]
	v_pk_fma_f32 v[74:75], v[88:89], v[94:95], v[74:75]
	v_pk_fma_f32 v[76:77], v[90:91], v[94:95], v[76:77] neg_lo:[0,0,1] neg_hi:[0,0,1]
	v_bfe_u32 v88, v74, 16, 1
	v_addc_co_u32_e32 v87, vcc, 0, v73, vcc
	v_bfe_u32 v89, v75, 16, 1
	v_bfe_u32 v90, v76, 16, 1
	v_add3_u32 v74, v74, v88, s44
	v_add_co_u32_e32 v92, vcc, s21, v0
	v_bfe_u32 v91, v77, 16, 1
	v_add3_u32 v75, v75, v89, s44
	v_add3_u32 v76, v76, v90, s44
	v_lshrrev_b32_e32 v74, 16, v74
	v_addc_co_u32_e32 v93, vcc, 0, v1, vcc
	v_add3_u32 v77, v77, v91, s44
	v_lshrrev_b32_e32 v76, 16, v76
	v_and_or_b32 v74, v75, s43, v74
	v_and_or_b32 v75, v77, s43, v76
	global_store_dword v[92:93], v74, off
	global_store_dword v[92:93], v75, off offset:512
	v_add_co_u32_e32 v72, vcc, s47, v72
	v_mov_b32_e32 v74, v228
	v_mov_b32_e32 v75, v229
	v_mov_b32_e32 v76, v230
	v_mov_b32_e32 v77, v231
	v_mov_b32_e32 v85, v76
	v_mov_b32_e32 v76, v75
	v_mov_b32_e32 v84, v74
	v_pk_mul_f32 v[74:75], v[80:81], v[76:77]
	v_pk_mul_f32 v[76:77], v[78:79], v[76:77]
	v_pk_fma_f32 v[74:75], v[78:79], v[84:85], v[74:75]
	v_pk_fma_f32 v[76:77], v[80:81], v[84:85], v[76:77] neg_lo:[0,0,1] neg_hi:[0,0,1]
	v_bfe_u32 v78, v74, 16, 1
	v_addc_co_u32_e32 v73, vcc, 0, v73, vcc
	v_bfe_u32 v79, v75, 16, 1
	v_bfe_u32 v80, v76, 16, 1
	v_add3_u32 v74, v74, v78, s44
	v_add_co_u32_e32 v82, vcc, s30, v0
	v_bfe_u32 v81, v77, 16, 1
	v_add3_u32 v75, v75, v79, s44
	v_add3_u32 v76, v76, v80, s44
	v_lshrrev_b32_e32 v74, 16, v74
	v_addc_co_u32_e32 v83, vcc, 0, v1, vcc
	v_add3_u32 v77, v77, v81, s44
	v_lshrrev_b32_e32 v76, 16, v76
	v_and_or_b32 v74, v75, s43, v74
	v_and_or_b32 v75, v77, s43, v76
	global_store_dword v[82:83], v74, off
	global_store_dword v[82:83], v75, off offset:512
	v_add_co_u32_e32 v56, vcc, s1, v0
	v_mov_b32_e32 v74, v176
	v_mov_b32_e32 v75, v177
	v_mov_b32_e32 v76, v178
	v_mov_b32_e32 v77, v179
	v_mov_b32_e32 v59, v76
	v_mov_b32_e32 v76, v75
	v_mov_b32_e32 v58, v74
	v_pk_mul_f32 v[74:75], v[30:31], v[76:77]
	v_pk_mul_f32 v[76:77], v[28:29], v[76:77]
	v_pk_fma_f32 v[28:29], v[28:29], v[58:59], v[74:75]
	v_pk_fma_f32 v[30:31], v[30:31], v[58:59], v[76:77] neg_lo:[0,0,1] neg_hi:[0,0,1]
	v_bfe_u32 v58, v28, 16, 1
	v_bfe_u32 v59, v29, 16, 1
	v_bfe_u32 v74, v30, 16, 1
	v_add3_u32 v28, v28, v58, s44
	v_bfe_u32 v75, v31, 16, 1
	v_add3_u32 v29, v29, v59, s44
	v_add3_u32 v30, v30, v74, s44
	v_lshrrev_b32_e32 v28, 16, v28
	v_addc_co_u32_e32 v57, vcc, 0, v1, vcc
	v_add3_u32 v31, v31, v75, s44
	v_lshrrev_b32_e32 v30, 16, v30
	v_and_or_b32 v28, v29, s43, v28
	v_and_or_b32 v29, v31, s43, v30
	global_store_dword v[56:57], v28, off
	global_store_dword v[56:57], v29, off offset:512
	v_add_co_u32_e32 v46, vcc, s15, v0
	v_mov_b32_e32 v28, v192
	v_mov_b32_e32 v29, v193
	v_mov_b32_e32 v30, v194
	v_mov_b32_e32 v31, v195
	v_mov_b32_e32 v49, v30
	v_mov_b32_e32 v30, v29
	v_mov_b32_e32 v48, v28
	v_pk_mul_f32 v[28:29], v[44:45], v[30:31]
	v_pk_mul_f32 v[30:31], v[40:41], v[30:31]
	v_pk_fma_f32 v[28:29], v[40:41], v[48:49], v[28:29]
	v_pk_fma_f32 v[30:31], v[44:45], v[48:49], v[30:31] neg_lo:[0,0,1] neg_hi:[0,0,1]
	v_bfe_u32 v40, v28, 16, 1
	v_bfe_u32 v41, v29, 16, 1
	v_bfe_u32 v44, v30, 16, 1
	v_add3_u32 v28, v28, v40, s44
	v_bfe_u32 v45, v31, 16, 1
	v_add3_u32 v29, v29, v41, s44
	v_add3_u32 v30, v30, v44, s44
	v_lshrrev_b32_e32 v28, 16, v28
	v_addc_co_u32_e32 v47, vcc, 0, v1, vcc
	v_add3_u32 v31, v31, v45, s44
	v_lshrrev_b32_e32 v30, 16, v30
	v_and_or_b32 v28, v29, s43, v28
	v_and_or_b32 v29, v31, s43, v30
	global_store_dword v[46:47], v28, off
	global_store_dword v[46:47], v29, off offset:512
	v_pk_add_f32 v[40:41], v[42:43], v[52:53] neg_lo:[0,1] neg_hi:[0,1]
	v_pk_add_f32 v[42:43], v[50:51], v[54:55] neg_lo:[0,1] neg_hi:[0,1]
	v_add_co_u32_e32 v44, vcc, s23, v0
	v_pk_add_f32 v[48:49], v[24:25], v[26:27] neg_lo:[0,1] neg_hi:[0,1]
	s_nop 0
	v_addc_co_u32_e32 v45, vcc, 0, v1, vcc
	v_add_co_u32_e32 v36, vcc, s31, v0
	v_pk_add_f32 v[50:51], v[12:13], v[16:17] neg_lo:[0,1] neg_hi:[0,1]
	s_nop 0
	v_addc_co_u32_e32 v37, vcc, 0, v1, vcc
	v_mov_b32_e32 v28, v216
	v_mov_b32_e32 v29, v217
	v_mov_b32_e32 v30, v218
	v_mov_b32_e32 v31, v219
	v_mov_b32_e32 v47, v30
	v_mov_b32_e32 v30, v29
	v_mov_b32_e32 v46, v28
	v_pk_mul_f32 v[28:29], v[42:43], v[30:31]
	v_pk_mul_f32 v[30:31], v[40:41], v[30:31]
	v_pk_fma_f32 v[28:29], v[40:41], v[46:47], v[28:29]
	v_pk_fma_f32 v[30:31], v[42:43], v[46:47], v[30:31] neg_lo:[0,0,1] neg_hi:[0,0,1]
	v_bfe_u32 v40, v28, 16, 1
	v_bfe_u32 v41, v29, 16, 1
	v_bfe_u32 v42, v30, 16, 1
	v_add3_u32 v28, v28, v40, s44
	v_bfe_u32 v43, v31, 16, 1
	v_add3_u32 v29, v29, v41, s44
	v_add3_u32 v30, v30, v42, s44
	v_lshrrev_b32_e32 v28, 16, v28
	v_add3_u32 v31, v31, v43, s44
	v_lshrrev_b32_e32 v30, 16, v30
	v_and_or_b32 v28, v29, s43, v28
	v_and_or_b32 v29, v31, s43, v30
	global_store_dword v[44:45], v28, off
	global_store_dword v[44:45], v29, off offset:512
	v_add_co_u32_e32 v40, vcc, s9, v0
	v_pk_add_f32 v[46:47], v[14:15], v[20:21] neg_lo:[0,1] neg_hi:[0,1]
	s_nop 0
	v_addc_co_u32_e32 v41, vcc, 0, v1, vcc
	s_waitcnt vmcnt(22)
	v_mov_b32_e32 v44, v135
	v_mov_b32_e32 v45, v136
	v_mov_b32_e32 v28, v232
	v_mov_b32_e32 v29, v233
	v_mov_b32_e32 v30, v234
	v_mov_b32_e32 v31, v235
	v_mov_b32_e32 v39, v30
	v_mov_b32_e32 v30, v29
	v_mov_b32_e32 v38, v28
	v_pk_mul_f32 v[28:29], v[34:35], v[30:31]
	v_pk_mul_f32 v[30:31], v[32:33], v[30:31]
	v_pk_fma_f32 v[28:29], v[32:33], v[38:39], v[28:29]
	v_pk_fma_f32 v[30:31], v[34:35], v[38:39], v[30:31] neg_lo:[0,0,1] neg_hi:[0,0,1]
	v_bfe_u32 v32, v28, 16, 1
	v_bfe_u32 v33, v29, 16, 1
	v_bfe_u32 v34, v30, 16, 1
	v_add3_u32 v28, v28, v32, s44
	v_bfe_u32 v35, v31, 16, 1
	v_add3_u32 v29, v29, v33, s44
	v_add3_u32 v30, v30, v34, s44
	v_lshrrev_b32_e32 v28, 16, v28
	v_add3_u32 v31, v31, v35, s44
	v_lshrrev_b32_e32 v30, 16, v30
	v_and_or_b32 v28, v29, s43, v28
	v_and_or_b32 v29, v31, s43, v30
	global_store_dword v[36:37], v28, off
	global_store_dword v[36:37], v29, off offset:512
	v_pk_add_f32 v[34:35], v[22:23], v[18:19]
	v_pk_add_f32 v[38:39], v[12:13], v[16:17]
	v_pk_add_f32 v[32:33], v[14:15], v[20:21]
	v_pk_add_f32 v[36:37], v[24:25], v[26:27]
	v_pk_add_f32 v[10:11], v[34:35], v[38:39]
	v_pk_add_f32 v[8:9], v[32:33], v[36:37]
	v_pk_add_f32 v[22:23], v[22:23], v[18:19] neg_lo:[0,1] neg_hi:[0,1]
	v_add_co_u32_e32 v14, vcc, s17, v0
	v_pk_add_f32 v[12:13], v[22:23], v[48:49] neg_lo:[0,1] neg_hi:[0,1]
	s_nop 0
	v_addc_co_u32_e32 v15, vcc, 0, v1, vcc
	v_pk_add_f32 v[22:23], v[22:23], v[48:49]
	v_mov_b32_e32 v27, v119
	v_mov_b32_e32 v25, v120
	v_mov_b32_e32 v28, v180
	v_mov_b32_e32 v29, v181
	v_mov_b32_e32 v30, v182
	v_mov_b32_e32 v31, v183
	v_mov_b32_e32 v43, v30
	v_mov_b32_e32 v30, v29
	v_mov_b32_e32 v42, v28
	v_pk_mul_f32 v[28:29], v[10:11], v[30:31]
	v_pk_mul_f32 v[30:31], v[8:9], v[30:31]
	v_pk_fma_f32 v[8:9], v[8:9], v[42:43], v[28:29]
	v_pk_fma_f32 v[10:11], v[10:11], v[42:43], v[30:31] neg_lo:[0,0,1] neg_hi:[0,0,1]
	v_bfe_u32 v28, v8, 16, 1
	v_bfe_u32 v29, v9, 16, 1
	v_bfe_u32 v30, v10, 16, 1
	v_add3_u32 v8, v8, v28, s44
	v_bfe_u32 v31, v11, 16, 1
	v_add3_u32 v9, v9, v29, s44
	v_add3_u32 v10, v10, v30, s44
	v_lshrrev_b32_e32 v8, 16, v8
	v_add3_u32 v11, v11, v31, s44
	v_lshrrev_b32_e32 v10, 16, v10
	v_and_or_b32 v8, v9, s43, v8
	v_and_or_b32 v9, v11, s43, v10
	global_store_dword v[40:41], v8, off
	global_store_dword v[40:41], v9, off offset:512
	v_pk_add_f32 v[4:5], v[46:47], v[50:51]
	v_mov_b32_e32 v41, v132
	v_mov_b32_e32 v42, v133
	v_mov_b32_e32 v43, v134
	v_mov_b32_e32 v30, v129
	v_mov_b32_e32 v31, v130
	v_mov_b32_e32 v40, v128
	v_mov_b32_e32 v28, v117
	v_mov_b32_e32 v29, v118
	v_mov_b32_e32 v8, v204
	v_mov_b32_e32 v9, v205
	v_mov_b32_e32 v10, v206
	v_mov_b32_e32 v11, v207
	v_mov_b32_e32 v17, v10
	v_mov_b32_e32 v10, v9
	v_mov_b32_e32 v16, v8
	v_pk_mul_f32 v[8:9], v[12:13], v[10:11]
	v_pk_mul_f32 v[10:11], v[4:5], v[10:11]
	v_pk_fma_f32 v[4:5], v[4:5], v[16:17], v[8:9]
	v_pk_fma_f32 v[8:9], v[12:13], v[16:17], v[10:11] neg_lo:[0,0,1] neg_hi:[0,0,1]
	v_bfe_u32 v10, v4, 16, 1
	v_bfe_u32 v11, v5, 16, 1
	v_bfe_u32 v12, v8, 16, 1
	v_add3_u32 v4, v4, v10, s44
	v_bfe_u32 v13, v9, 16, 1
	v_add3_u32 v5, v5, v11, s44
	v_add3_u32 v8, v8, v12, s44
	v_lshrrev_b32_e32 v4, 16, v4
	v_add3_u32 v9, v9, v13, s44
	v_lshrrev_b32_e32 v8, 16, v8
	v_and_or_b32 v4, v5, s43, v4
	v_and_or_b32 v5, v9, s43, v8
	global_store_dword v[14:15], v4, off
	global_store_dword v[14:15], v5, off offset:512
	v_pk_add_f32 v[10:11], v[34:35], v[38:39] neg_lo:[0,1] neg_hi:[0,1]
	v_pk_add_f32 v[8:9], v[32:33], v[36:37] neg_lo:[0,1] neg_hi:[0,1]
	v_add_co_u32_e32 v12, vcc, s28, v0
	v_mov_b32_e32 v36, v137
	s_nop 0
	v_addc_co_u32_e32 v13, vcc, 0, v1, vcc
	v_add_co_u32_e32 v0, vcc, s34, v0
	v_mov_b32_e32 v38, v138
	s_nop 0
	v_addc_co_u32_e32 v1, vcc, 0, v1, vcc
	v_mov_b32_e32 v39, v131
	v_mov_b32_e32 v32, v123
	v_mov_b32_e32 v33, v124
	v_mov_b32_e32 v34, v125
	v_mov_b32_e32 v35, v126
	v_mov_b32_e32 v37, v127
	v_mov_b32_e32 v17, v113
	s_andn2_b64 vcc, exec, s[24:25]
	v_mov_b32_e32 v2, v220
	v_mov_b32_e32 v3, v221
	v_mov_b32_e32 v4, v222
	v_mov_b32_e32 v5, v223
	v_mov_b32_e32 v15, v4
	v_mov_b32_e32 v4, v3
	v_mov_b32_e32 v14, v2
	v_pk_mul_f32 v[2:3], v[10:11], v[4:5]
	v_pk_mul_f32 v[4:5], v[8:9], v[4:5]
	v_pk_fma_f32 v[2:3], v[8:9], v[14:15], v[2:3]
	v_pk_fma_f32 v[4:5], v[10:11], v[14:15], v[4:5] neg_lo:[0,0,1] neg_hi:[0,0,1]
	v_bfe_u32 v8, v2, 16, 1
	v_bfe_u32 v9, v3, 16, 1
	v_bfe_u32 v10, v4, 16, 1
	v_add3_u32 v2, v2, v8, s44
	v_bfe_u32 v11, v5, 16, 1
	v_add3_u32 v3, v3, v9, s44
	v_add3_u32 v4, v4, v10, s44
	v_lshrrev_b32_e32 v2, 16, v2
	v_add3_u32 v5, v5, v11, s44
	v_lshrrev_b32_e32 v4, 16, v4
	v_and_or_b32 v2, v3, s43, v2
	v_and_or_b32 v3, v5, s43, v4
	global_store_dword v[12:13], v2, off
	global_store_dword v[12:13], v3, off offset:512
	v_pk_add_f32 v[2:3], v[46:47], v[50:51] neg_lo:[0,1] neg_hi:[0,1]
	v_mov_b32_e32 v4, v121
	v_mov_b32_e32 v5, v122
	v_mov_b32_e32 v6, v115
	v_mov_b32_e32 v7, v116
	v_mov_b32_e32 v9, v114
	v_mov_b32_e32 v8, v107
	v_mov_b32_e32 v11, v108
	v_mov_b32_e32 v10, v109
	v_mov_b32_e32 v13, v110
	v_mov_b32_e32 v12, v111
	v_mov_b32_e32 v15, v112
	v_mov_b32_e32 v18, v236
	v_mov_b32_e32 v19, v237
	v_mov_b32_e32 v20, v238
	v_mov_b32_e32 v21, v239
	v_mov_b32_e32 v47, v20
	v_mov_b32_e32 v20, v19
	v_mov_b32_e32 v46, v18
	v_pk_mul_f32 v[18:19], v[22:23], v[20:21]
	v_pk_mul_f32 v[20:21], v[2:3], v[20:21]
	v_pk_fma_f32 v[2:3], v[2:3], v[46:47], v[18:19]
	v_pk_fma_f32 v[18:19], v[22:23], v[46:47], v[20:21] neg_lo:[0,0,1] neg_hi:[0,0,1]
	v_bfe_u32 v14, v2, 16, 1
	v_bfe_u32 v16, v3, 16, 1
	v_bfe_u32 v20, v18, 16, 1
	v_add3_u32 v2, v2, v14, s44
	v_bfe_u32 v21, v19, 16, 1
	v_add3_u32 v3, v3, v16, s44
	v_add3_u32 v14, v18, v20, s44
	v_lshrrev_b32_e32 v2, 16, v2
	v_add3_u32 v16, v19, v21, s44
	v_lshrrev_b32_e32 v14, 16, v14
	v_and_or_b32 v2, v3, s43, v2
	v_and_or_b32 v3, v16, s43, v14
	global_store_dword v[0:1], v2, off
	global_store_dword v[0:1], v3, off offset:512
	s_cbranch_vccz .LBB0_237

.LBB0_388:
	v_lshl_add_u32 v188, s34, 8, v137
	v_lshlrev_b32_e32 v253, 2, v188
	v_lshlrev_b32_e32 v188, 11, v188
	v_lshl_add_u32 v188, s30, 8, v188
	v_or_b32_e32 v252, v188, v136
	v_lshlrev_b32_e32 v251, 1, v252
	v_lshlrev_b32_e32 v250, 2, v252
	v_xor_b32_e32 v254, 16, v167
	v_xor_b32_e32 v255, 32, v167
	v_lshlrev_b32_e32 v254, 2, v254
	v_lshlrev_b32_e32 v255, 2, v255
	v_mov_b32_e32 v192, v250
	global_load_dwordx4 v[204:207], v192, s[36:37] offset:0
	global_load_dwordx4 v[208:211], v192, s[36:37] offset:16
	global_load_dwordx4 v[212:215], v192, s[36:37] offset:512
	global_load_dwordx4 v[216:219], v192, s[36:37] offset:528
	v_add_u32_e32 v192, 0x20000, v250
	global_load_dwordx4 v[220:223], v192, s[36:37] offset:0
	global_load_dwordx4 v[224:227], v192, s[36:37] offset:16
	global_load_dwordx4 v[228:231], v192, s[36:37] offset:512
	global_load_dwordx4 v[232:235], v192, s[36:37] offset:528
	v_add_u32_e32 v192, 0x40000, v250
	global_load_dwordx4 v[236:239], v192, s[36:37] offset:0
	global_load_dwordx4 v[240:243], v192, s[36:37] offset:16
	global_load_dwordx4 v[244:247], v192, s[36:37] offset:512
	global_load_dwordx4 v[168:171], v192, s[36:37] offset:528
	v_add_u32_e32 v192, 0x60000, v250
	global_load_dwordx4 v[172:175], v192, s[36:37] offset:0
	global_load_dwordx4 v[176:179], v192, s[36:37] offset:16
	global_load_dwordx4 v[180:183], v192, s[36:37] offset:512
	global_load_dwordx4 v[184:187], v192, s[36:37] offset:528
	s_waitcnt vmcnt(14)
	v_pk_add_f32 v[124:125], v[124:125], v[204:205]
	v_pk_add_f32 v[126:127], v[126:127], v[206:207]
	v_pk_add_f32 v[120:121], v[120:121], v[208:209]
	v_pk_add_f32 v[122:123], v[122:123], v[210:211]
	v_cvt_pk_bf16_f32 v188, v124, v125
	v_cvt_pk_bf16_f32 v189, v126, v127
	v_cvt_pk_bf16_f32 v190, v120, v121
	v_cvt_pk_bf16_f32 v191, v122, v123
	v_cvt_pk_fp8_f32 v192, v124, v125
	v_cvt_pk_fp8_f32 v193, v120, v121
	v_cvt_pk_fp8_f32 v192, v126, v127 op_sel:[0,0,1]
	v_cvt_pk_fp8_f32 v193, v122, v123 op_sel:[0,0,1]
	v_mov_b32_e32 v204, v251
	v_mov_b32_e32 v205, v252
	global_store_dwordx4 v204, v[188:191], s[68:69] offset:0
	global_store_dwordx2 v205, v[192:193], s[14:15] offset:0
	v_mul_f32_e32 v125, v125, v125
	v_mul_f32_e32 v127, v127, v127
	v_mul_f32_e32 v121, v121, v121
	v_mul_f32_e32 v123, v123, v123
	v_fmac_f32_e32 v125, v124, v124
	v_fmac_f32_e32 v127, v126, v126
	v_fmac_f32_e32 v121, v120, v120
	v_fmac_f32_e32 v123, v122, v122
	v_add_f32_e32 v125, v125, v127
	v_add_f32_e32 v125, v125, v121
	v_add_f32_e32 v194, v123, v125
	s_waitcnt vmcnt(14)
	v_pk_add_f32 v[116:117], v[116:117], v[212:213]
	v_pk_add_f32 v[118:119], v[118:119], v[214:215]
	v_pk_add_f32 v[112:113], v[112:113], v[216:217]
	v_pk_add_f32 v[114:115], v[114:115], v[218:219]
	v_cvt_pk_bf16_f32 v188, v116, v117
	v_cvt_pk_bf16_f32 v189, v118, v119
	v_cvt_pk_bf16_f32 v190, v112, v113
	v_cvt_pk_bf16_f32 v191, v114, v115
	v_cvt_pk_fp8_f32 v192, v116, v117
	v_cvt_pk_fp8_f32 v193, v112, v113
	v_cvt_pk_fp8_f32 v192, v118, v119 op_sel:[0,0,1]
	v_cvt_pk_fp8_f32 v193, v114, v115 op_sel:[0,0,1]
	v_mov_b32_e32 v212, v251
	v_mov_b32_e32 v213, v252
	global_store_dwordx4 v212, v[188:191], s[68:69] offset:256
	global_store_dwordx2 v213, v[192:193], s[14:15] offset:128
	v_mul_f32_e32 v117, v117, v117
	v_mul_f32_e32 v119, v119, v119
	v_mul_f32_e32 v113, v113, v113
	v_mul_f32_e32 v115, v115, v115
	v_fmac_f32_e32 v117, v116, v116
	v_fmac_f32_e32 v119, v118, v118
	v_fmac_f32_e32 v113, v112, v112
	v_fmac_f32_e32 v115, v114, v114
	v_add_f32_e32 v117, v117, v119
	v_add_f32_e32 v117, v117, v113
	v_add_f32_e32 v117, v115, v117
	v_add_f32_e32 v194, v194, v117
	v_add_u32_e32 v192, 0x100000, v250
	global_load_dwordx4 v[204:207], v192, s[36:37] offset:0
	global_load_dwordx4 v[208:211], v192, s[36:37] offset:16
	global_load_dwordx4 v[212:215], v192, s[36:37] offset:512
	global_load_dwordx4 v[216:219], v192, s[36:37] offset:528
	s_waitcnt vmcnt(18)
	v_pk_add_f32 v[108:109], v[108:109], v[220:221]
	v_pk_add_f32 v[110:111], v[110:111], v[222:223]
	v_pk_add_f32 v[104:105], v[104:105], v[224:225]
	v_pk_add_f32 v[106:107], v[106:107], v[226:227]
	v_cvt_pk_bf16_f32 v188, v108, v109
	v_cvt_pk_bf16_f32 v189, v110, v111
	v_cvt_pk_bf16_f32 v190, v104, v105
	v_cvt_pk_bf16_f32 v191, v106, v107
	v_cvt_pk_fp8_f32 v192, v108, v109
	v_cvt_pk_fp8_f32 v193, v104, v105
	v_cvt_pk_fp8_f32 v192, v110, v111 op_sel:[0,0,1]
	v_cvt_pk_fp8_f32 v193, v106, v107 op_sel:[0,0,1]
	v_add_u32_e32 v220, 0x10000, v251
	v_add_u32_e32 v221, 0x8000, v252
	global_store_dwordx4 v220, v[188:191], s[68:69] offset:0
	global_store_dwordx2 v221, v[192:193], s[14:15] offset:0
	v_mul_f32_e32 v109, v109, v109
	v_mul_f32_e32 v111, v111, v111
	v_mul_f32_e32 v105, v105, v105
	v_mul_f32_e32 v107, v107, v107
	v_fmac_f32_e32 v109, v108, v108
	v_fmac_f32_e32 v111, v110, v110
	v_fmac_f32_e32 v105, v104, v104
	v_fmac_f32_e32 v107, v106, v106
	v_add_f32_e32 v109, v109, v111
	v_add_f32_e32 v109, v109, v105
	v_add_f32_e32 v195, v107, v109
	s_waitcnt vmcnt(18)
	v_pk_add_f32 v[100:101], v[100:101], v[228:229]
	v_pk_add_f32 v[102:103], v[102:103], v[230:231]
	v_pk_add_f32 v[96:97], v[96:97], v[232:233]
	v_pk_add_f32 v[98:99], v[98:99], v[234:235]
	v_cvt_pk_bf16_f32 v188, v100, v101
	v_cvt_pk_bf16_f32 v189, v102, v103
	v_cvt_pk_bf16_f32 v190, v96, v97
	v_cvt_pk_bf16_f32 v191, v98, v99
	v_cvt_pk_fp8_f32 v192, v100, v101
	v_cvt_pk_fp8_f32 v193, v96, v97
	v_cvt_pk_fp8_f32 v192, v102, v103 op_sel:[0,0,1]
	v_cvt_pk_fp8_f32 v193, v98, v99 op_sel:[0,0,1]
	v_add_u32_e32 v228, 0x10000, v251
	v_add_u32_e32 v229, 0x8000, v252
	global_store_dwordx4 v228, v[188:191], s[68:69] offset:256
	global_store_dwordx2 v229, v[192:193], s[14:15] offset:128
	v_mul_f32_e32 v101, v101, v101
	v_mul_f32_e32 v103, v103, v103
	v_mul_f32_e32 v97, v97, v97
	v_mul_f32_e32 v99, v99, v99
	v_fmac_f32_e32 v101, v100, v100
	v_fmac_f32_e32 v103, v102, v102
	v_fmac_f32_e32 v97, v96, v96
	v_fmac_f32_e32 v99, v98, v98
	v_add_f32_e32 v101, v101, v103
	v_add_f32_e32 v101, v101, v97
	v_add_f32_e32 v101, v99, v101
	v_add_f32_e32 v195, v195, v101
	v_add_u32_e32 v192, 0x120000, v250
	global_load_dwordx4 v[220:223], v192, s[36:37] offset:0
	global_load_dwordx4 v[224:227], v192, s[36:37] offset:16
	global_load_dwordx4 v[228:231], v192, s[36:37] offset:512
	global_load_dwordx4 v[232:235], v192, s[36:37] offset:528
	s_waitcnt vmcnt(22)
	v_pk_add_f32 v[92:93], v[92:93], v[236:237]
	v_pk_add_f32 v[94:95], v[94:95], v[238:239]
	v_pk_add_f32 v[88:89], v[88:89], v[240:241]
	v_pk_add_f32 v[90:91], v[90:91], v[242:243]
	v_cvt_pk_bf16_f32 v188, v92, v93
	v_cvt_pk_bf16_f32 v189, v94, v95
	v_cvt_pk_bf16_f32 v190, v88, v89
	v_cvt_pk_bf16_f32 v191, v90, v91
	v_cvt_pk_fp8_f32 v192, v92, v93
	v_cvt_pk_fp8_f32 v193, v88, v89
	v_cvt_pk_fp8_f32 v192, v94, v95 op_sel:[0,0,1]
	v_cvt_pk_fp8_f32 v193, v90, v91 op_sel:[0,0,1]
	v_add_u32_e32 v236, 0x20000, v251
	v_add_u32_e32 v237, 0x10000, v252
	global_store_dwordx4 v236, v[188:191], s[68:69] offset:0
	global_store_dwordx2 v237, v[192:193], s[14:15] offset:0
	v_mul_f32_e32 v93, v93, v93
	v_mul_f32_e32 v95, v95, v95
	v_mul_f32_e32 v89, v89, v89
	v_mul_f32_e32 v91, v91, v91
	v_fmac_f32_e32 v93, v92, v92
	v_fmac_f32_e32 v95, v94, v94
	v_fmac_f32_e32 v89, v88, v88
	v_fmac_f32_e32 v91, v90, v90
	v_add_f32_e32 v93, v93, v95
	v_add_f32_e32 v93, v93, v89
	v_add_f32_e32 v196, v91, v93
	s_waitcnt vmcnt(22)
	v_pk_add_f32 v[84:85], v[84:85], v[244:245]
	v_pk_add_f32 v[86:87], v[86:87], v[246:247]
	v_pk_add_f32 v[80:81], v[80:81], v[168:169]
	v_pk_add_f32 v[82:83], v[82:83], v[170:171]
	v_cvt_pk_bf16_f32 v188, v84, v85
	v_cvt_pk_bf16_f32 v189, v86, v87
	v_cvt_pk_bf16_f32 v190, v80, v81
	v_cvt_pk_bf16_f32 v191, v82, v83
	v_cvt_pk_fp8_f32 v192, v84, v85
	v_cvt_pk_fp8_f32 v193, v80, v81
	v_cvt_pk_fp8_f32 v192, v86, v87 op_sel:[0,0,1]
	v_cvt_pk_fp8_f32 v193, v82, v83 op_sel:[0,0,1]
	v_add_u32_e32 v244, 0x20000, v251
	v_add_u32_e32 v245, 0x10000, v252
	global_store_dwordx4 v244, v[188:191], s[68:69] offset:256
	global_store_dwordx2 v245, v[192:193], s[14:15] offset:128
	v_mul_f32_e32 v85, v85, v85
	v_mul_f32_e32 v87, v87, v87
	v_mul_f32_e32 v81, v81, v81
	v_mul_f32_e32 v83, v83, v83
	v_fmac_f32_e32 v85, v84, v84
	v_fmac_f32_e32 v87, v86, v86
	v_fmac_f32_e32 v81, v80, v80
	v_fmac_f32_e32 v83, v82, v82
	v_add_f32_e32 v85, v85, v87
	v_add_f32_e32 v85, v85, v81
	v_add_f32_e32 v85, v83, v85
	v_add_f32_e32 v196, v196, v85
	v_add_u32_e32 v192, 0x140000, v250
	global_load_dwordx4 v[236:239], v192, s[36:37] offset:0
	global_load_dwordx4 v[240:243], v192, s[36:37] offset:16
	global_load_dwordx4 v[244:247], v192, s[36:37] offset:512
	global_load_dwordx4 v[168:171], v192, s[36:37] offset:528
	s_waitcnt vmcnt(26)
	v_pk_add_f32 v[76:77], v[76:77], v[172:173]
	v_pk_add_f32 v[78:79], v[78:79], v[174:175]
	v_pk_add_f32 v[72:73], v[72:73], v[176:177]
	v_pk_add_f32 v[74:75], v[74:75], v[178:179]
	v_cvt_pk_bf16_f32 v188, v76, v77
	v_cvt_pk_bf16_f32 v189, v78, v79
	v_cvt_pk_bf16_f32 v190, v72, v73
	v_cvt_pk_bf16_f32 v191, v74, v75
	v_cvt_pk_fp8_f32 v192, v76, v77
	v_cvt_pk_fp8_f32 v193, v72, v73
	v_cvt_pk_fp8_f32 v192, v78, v79 op_sel:[0,0,1]
	v_cvt_pk_fp8_f32 v193, v74, v75 op_sel:[0,0,1]
	v_add_u32_e32 v172, 0x30000, v251
	v_add_u32_e32 v173, 0x18000, v252
	global_store_dwordx4 v172, v[188:191], s[68:69] offset:0
	global_store_dwordx2 v173, v[192:193], s[14:15] offset:0
	v_mul_f32_e32 v77, v77, v77
	v_mul_f32_e32 v79, v79, v79
	v_mul_f32_e32 v73, v73, v73
	v_mul_f32_e32 v75, v75, v75
	v_fmac_f32_e32 v77, v76, v76
	v_fmac_f32_e32 v79, v78, v78
	v_fmac_f32_e32 v73, v72, v72
	v_fmac_f32_e32 v75, v74, v74
	v_add_f32_e32 v77, v77, v79
	v_add_f32_e32 v77, v77, v73
	v_add_f32_e32 v249, v75, v77
	s_waitcnt vmcnt(26)
	v_pk_add_f32 v[68:69], v[68:69], v[180:181]
	v_pk_add_f32 v[70:71], v[70:71], v[182:183]
	v_pk_add_f32 v[64:65], v[64:65], v[184:185]
	v_pk_add_f32 v[66:67], v[66:67], v[186:187]
	v_cvt_pk_bf16_f32 v188, v68, v69
	v_cvt_pk_bf16_f32 v189, v70, v71
	v_cvt_pk_bf16_f32 v190, v64, v65
	v_cvt_pk_bf16_f32 v191, v66, v67
	v_cvt_pk_fp8_f32 v192, v68, v69
	v_cvt_pk_fp8_f32 v193, v64, v65
	v_cvt_pk_fp8_f32 v192, v70, v71 op_sel:[0,0,1]
	v_cvt_pk_fp8_f32 v193, v66, v67 op_sel:[0,0,1]
	v_add_u32_e32 v180, 0x30000, v251
	v_add_u32_e32 v181, 0x18000, v252
	global_store_dwordx4 v180, v[188:191], s[68:69] offset:256
	global_store_dwordx2 v181, v[192:193], s[14:15] offset:128
	v_mul_f32_e32 v69, v69, v69
	v_mul_f32_e32 v71, v71, v71
	v_mul_f32_e32 v65, v65, v65
	v_mul_f32_e32 v67, v67, v67
	v_fmac_f32_e32 v69, v68, v68
	v_fmac_f32_e32 v71, v70, v70
	v_fmac_f32_e32 v65, v64, v64
	v_fmac_f32_e32 v67, v66, v66
	v_add_f32_e32 v69, v69, v71
	v_add_f32_e32 v69, v69, v65
	v_add_f32_e32 v69, v67, v69
	v_add_f32_e32 v249, v249, v69
	v_add_u32_e32 v192, 0x160000, v250
	global_load_dwordx4 v[172:175], v192, s[36:37] offset:0
	global_load_dwordx4 v[176:179], v192, s[36:37] offset:16
	global_load_dwordx4 v[180:183], v192, s[36:37] offset:512
	global_load_dwordx4 v[184:187], v192, s[36:37] offset:528
	ds_bpermute_b32 v188, v254, v194
	ds_bpermute_b32 v189, v254, v195
	ds_bpermute_b32 v190, v254, v196
	ds_bpermute_b32 v191, v254, v249
	s_waitcnt lgkmcnt(0)
	v_add_f32_e32 v194, v194, v188
	v_add_f32_e32 v195, v195, v189
	v_add_f32_e32 v196, v196, v190
	v_add_f32_e32 v249, v249, v191
	ds_bpermute_b32 v188, v255, v194
	ds_bpermute_b32 v189, v255, v195
	ds_bpermute_b32 v190, v255, v196
	ds_bpermute_b32 v191, v255, v249
	s_waitcnt lgkmcnt(0)
	v_add_f32_e32 v194, v194, v188
	v_add_f32_e32 v195, v195, v189
	v_add_f32_e32 v196, v196, v190
	v_add_f32_e32 v249, v249, v191
	s_and_saveexec_b64 s[30:31], s[4:5]
	global_atomic_add_f32 v253, v194, s[12:13] offset:0
	global_atomic_add_f32 v253, v195, s[12:13] offset:64
	global_atomic_add_f32 v253, v196, s[12:13] offset:128
	global_atomic_add_f32 v253, v249, s[12:13] offset:192
	s_or_b64 exec, exec, s[30:31]
	s_waitcnt vmcnt(30)
	v_pk_add_f32 v[60:61], v[60:61], v[204:205]
	v_pk_add_f32 v[62:63], v[62:63], v[206:207]
	v_pk_add_f32 v[56:57], v[56:57], v[208:209]
	v_pk_add_f32 v[58:59], v[58:59], v[210:211]
	v_cvt_pk_bf16_f32 v188, v60, v61
	v_cvt_pk_bf16_f32 v189, v62, v63
	v_cvt_pk_bf16_f32 v190, v56, v57
	v_cvt_pk_bf16_f32 v191, v58, v59
	v_cvt_pk_fp8_f32 v192, v60, v61
	v_cvt_pk_fp8_f32 v193, v56, v57
	v_cvt_pk_fp8_f32 v192, v62, v63 op_sel:[0,0,1]
	v_cvt_pk_fp8_f32 v193, v58, v59 op_sel:[0,0,1]
	v_add_u32_e32 v204, 0x80000, v251
	v_add_u32_e32 v205, 0x40000, v252
	global_store_dwordx4 v204, v[188:191], s[68:69] offset:0
	global_store_dwordx2 v205, v[192:193], s[14:15] offset:0
	v_mul_f32_e32 v61, v61, v61
	v_mul_f32_e32 v63, v63, v63
	v_mul_f32_e32 v57, v57, v57
	v_mul_f32_e32 v59, v59, v59
	v_fmac_f32_e32 v61, v60, v60
	v_fmac_f32_e32 v63, v62, v62
	v_fmac_f32_e32 v57, v56, v56
	v_fmac_f32_e32 v59, v58, v58
	v_add_f32_e32 v61, v61, v63
	v_add_f32_e32 v61, v61, v57
	v_add_f32_e32 v194, v59, v61
	s_waitcnt vmcnt(30)
	v_pk_add_f32 v[52:53], v[52:53], v[212:213]
	v_pk_add_f32 v[54:55], v[54:55], v[214:215]
	v_pk_add_f32 v[48:49], v[48:49], v[216:217]
	v_pk_add_f32 v[50:51], v[50:51], v[218:219]
	v_cvt_pk_bf16_f32 v188, v52, v53
	v_cvt_pk_bf16_f32 v189, v54, v55
	v_cvt_pk_bf16_f32 v190, v48, v49
	v_cvt_pk_bf16_f32 v191, v50, v51
	v_cvt_pk_fp8_f32 v192, v52, v53
	v_cvt_pk_fp8_f32 v193, v48, v49
	v_cvt_pk_fp8_f32 v192, v54, v55 op_sel:[0,0,1]
	v_cvt_pk_fp8_f32 v193, v50, v51 op_sel:[0,0,1]
	v_add_u32_e32 v212, 0x80000, v251
	v_add_u32_e32 v213, 0x40000, v252
	global_store_dwordx4 v212, v[188:191], s[68:69] offset:256
	global_store_dwordx2 v213, v[192:193], s[14:15] offset:128
	v_mul_f32_e32 v53, v53, v53
	v_mul_f32_e32 v55, v55, v55
	v_mul_f32_e32 v49, v49, v49
	v_mul_f32_e32 v51, v51, v51
	v_fmac_f32_e32 v53, v52, v52
	v_fmac_f32_e32 v55, v54, v54
	v_fmac_f32_e32 v49, v48, v48
	v_fmac_f32_e32 v51, v50, v50
	v_add_f32_e32 v53, v53, v55
	v_add_f32_e32 v53, v53, v49
	v_add_f32_e32 v53, v51, v53
	v_add_f32_e32 v194, v194, v53
	s_waitcnt vmcnt(26)
	v_pk_add_f32 v[44:45], v[44:45], v[220:221]
	v_pk_add_f32 v[46:47], v[46:47], v[222:223]
	v_pk_add_f32 v[40:41], v[40:41], v[224:225]
	v_pk_add_f32 v[42:43], v[42:43], v[226:227]
	v_cvt_pk_bf16_f32 v188, v44, v45
	v_cvt_pk_bf16_f32 v189, v46, v47
	v_cvt_pk_bf16_f32 v190, v40, v41
	v_cvt_pk_bf16_f32 v191, v42, v43
	v_cvt_pk_fp8_f32 v192, v44, v45
	v_cvt_pk_fp8_f32 v193, v40, v41
	v_cvt_pk_fp8_f32 v192, v46, v47 op_sel:[0,0,1]
	v_cvt_pk_fp8_f32 v193, v42, v43 op_sel:[0,0,1]
	v_add_u32_e32 v220, 0x90000, v251
	v_add_u32_e32 v221, 0x48000, v252
	global_store_dwordx4 v220, v[188:191], s[68:69] offset:0
	global_store_dwordx2 v221, v[192:193], s[14:15] offset:0
	v_mul_f32_e32 v45, v45, v45
	v_mul_f32_e32 v47, v47, v47
	v_mul_f32_e32 v41, v41, v41
	v_mul_f32_e32 v43, v43, v43
	v_fmac_f32_e32 v45, v44, v44
	v_fmac_f32_e32 v47, v46, v46
	v_fmac_f32_e32 v41, v40, v40
	v_fmac_f32_e32 v43, v42, v42
	v_add_f32_e32 v45, v45, v47
	v_add_f32_e32 v45, v45, v41
	v_add_f32_e32 v195, v43, v45
	s_waitcnt vmcnt(26)
	v_pk_add_f32 v[36:37], v[36:37], v[228:229]
	v_pk_add_f32 v[38:39], v[38:39], v[230:231]
	v_pk_add_f32 v[32:33], v[32:33], v[232:233]
	v_pk_add_f32 v[34:35], v[34:35], v[234:235]
	v_cvt_pk_bf16_f32 v188, v36, v37
	v_cvt_pk_bf16_f32 v189, v38, v39
	v_cvt_pk_bf16_f32 v190, v32, v33
	v_cvt_pk_bf16_f32 v191, v34, v35
	v_cvt_pk_fp8_f32 v192, v36, v37
	v_cvt_pk_fp8_f32 v193, v32, v33
	v_cvt_pk_fp8_f32 v192, v38, v39 op_sel:[0,0,1]
	v_cvt_pk_fp8_f32 v193, v34, v35 op_sel:[0,0,1]
	v_add_u32_e32 v228, 0x90000, v251
	v_add_u32_e32 v229, 0x48000, v252
	global_store_dwordx4 v228, v[188:191], s[68:69] offset:256
	global_store_dwordx2 v229, v[192:193], s[14:15] offset:128
	v_mul_f32_e32 v37, v37, v37
	v_mul_f32_e32 v39, v39, v39
	v_mul_f32_e32 v33, v33, v33
	v_mul_f32_e32 v35, v35, v35
	v_fmac_f32_e32 v37, v36, v36
	v_fmac_f32_e32 v39, v38, v38
	v_fmac_f32_e32 v33, v32, v32
	v_fmac_f32_e32 v35, v34, v34
	v_add_f32_e32 v37, v37, v39
	v_add_f32_e32 v37, v37, v33
	v_add_f32_e32 v37, v35, v37
	v_add_f32_e32 v195, v195, v37
	s_waitcnt vmcnt(22)
	v_pk_add_f32 v[28:29], v[28:29], v[236:237]
	v_pk_add_f32 v[30:31], v[30:31], v[238:239]
	v_pk_add_f32 v[24:25], v[24:25], v[240:241]
	v_pk_add_f32 v[26:27], v[26:27], v[242:243]
	v_cvt_pk_bf16_f32 v188, v28, v29
	v_cvt_pk_bf16_f32 v189, v30, v31
	v_cvt_pk_bf16_f32 v190, v24, v25
	v_cvt_pk_bf16_f32 v191, v26, v27
	v_cvt_pk_fp8_f32 v192, v28, v29
	v_cvt_pk_fp8_f32 v193, v24, v25
	v_cvt_pk_fp8_f32 v192, v30, v31 op_sel:[0,0,1]
	v_cvt_pk_fp8_f32 v193, v26, v27 op_sel:[0,0,1]
	v_add_u32_e32 v236, 0xa0000, v251
	v_add_u32_e32 v237, 0x50000, v252
	global_store_dwordx4 v236, v[188:191], s[68:69] offset:0
	global_store_dwordx2 v237, v[192:193], s[14:15] offset:0
	v_mul_f32_e32 v29, v29, v29
	v_mul_f32_e32 v31, v31, v31
	v_mul_f32_e32 v25, v25, v25
	v_mul_f32_e32 v27, v27, v27
	v_fmac_f32_e32 v29, v28, v28
	v_fmac_f32_e32 v31, v30, v30
	v_fmac_f32_e32 v25, v24, v24
	v_fmac_f32_e32 v27, v26, v26
	v_add_f32_e32 v29, v29, v31
	v_add_f32_e32 v29, v29, v25
	v_add_f32_e32 v196, v27, v29
	s_waitcnt vmcnt(22)
	v_pk_add_f32 v[20:21], v[20:21], v[244:245]
	v_pk_add_f32 v[22:23], v[22:23], v[246:247]
	v_pk_add_f32 v[16:17], v[16:17], v[168:169]
	v_pk_add_f32 v[18:19], v[18:19], v[170:171]
	v_cvt_pk_bf16_f32 v188, v20, v21
	v_cvt_pk_bf16_f32 v189, v22, v23
	v_cvt_pk_bf16_f32 v190, v16, v17
	v_cvt_pk_bf16_f32 v191, v18, v19
	v_cvt_pk_fp8_f32 v192, v20, v21
	v_cvt_pk_fp8_f32 v193, v16, v17
	v_cvt_pk_fp8_f32 v192, v22, v23 op_sel:[0,0,1]
	v_cvt_pk_fp8_f32 v193, v18, v19 op_sel:[0,0,1]
	v_add_u32_e32 v244, 0xa0000, v251
	v_add_u32_e32 v245, 0x50000, v252
	global_store_dwordx4 v244, v[188:191], s[68:69] offset:256
	global_store_dwordx2 v245, v[192:193], s[14:15] offset:128
	v_mul_f32_e32 v21, v21, v21
	v_mul_f32_e32 v23, v23, v23
	v_mul_f32_e32 v17, v17, v17
	v_mul_f32_e32 v19, v19, v19
	v_fmac_f32_e32 v21, v20, v20
	v_fmac_f32_e32 v23, v22, v22
	v_fmac_f32_e32 v17, v16, v16
	v_fmac_f32_e32 v19, v18, v18
	v_add_f32_e32 v21, v21, v23
	v_add_f32_e32 v21, v21, v17
	v_add_f32_e32 v21, v19, v21
	v_add_f32_e32 v196, v196, v21
	s_waitcnt vmcnt(18)
	v_pk_add_f32 v[12:13], v[12:13], v[172:173]
	v_pk_add_f32 v[14:15], v[14:15], v[174:175]
	v_pk_add_f32 v[8:9], v[8:9], v[176:177]
	v_pk_add_f32 v[10:11], v[10:11], v[178:179]
	v_cvt_pk_bf16_f32 v188, v12, v13
	v_cvt_pk_bf16_f32 v189, v14, v15
	v_cvt_pk_bf16_f32 v190, v8, v9
	v_cvt_pk_bf16_f32 v191, v10, v11
	v_cvt_pk_fp8_f32 v192, v12, v13
	v_cvt_pk_fp8_f32 v193, v8, v9
	v_cvt_pk_fp8_f32 v192, v14, v15 op_sel:[0,0,1]
	v_cvt_pk_fp8_f32 v193, v10, v11 op_sel:[0,0,1]
	v_add_u32_e32 v172, 0xb0000, v251
	v_add_u32_e32 v173, 0x58000, v252
	global_store_dwordx4 v172, v[188:191], s[68:69] offset:0
	global_store_dwordx2 v173, v[192:193], s[14:15] offset:0
	v_mul_f32_e32 v13, v13, v13
	v_mul_f32_e32 v15, v15, v15
	v_mul_f32_e32 v9, v9, v9
	v_mul_f32_e32 v11, v11, v11
	v_fmac_f32_e32 v13, v12, v12
	v_fmac_f32_e32 v15, v14, v14
	v_fmac_f32_e32 v9, v8, v8
	v_fmac_f32_e32 v11, v10, v10
	v_add_f32_e32 v13, v13, v15
	v_add_f32_e32 v13, v13, v9
	v_add_f32_e32 v249, v11, v13
	s_waitcnt vmcnt(18)
	v_pk_add_f32 v[4:5], v[4:5], v[180:181]
	v_pk_add_f32 v[6:7], v[6:7], v[182:183]
	v_pk_add_f32 v[0:1], v[0:1], v[184:185]
	v_pk_add_f32 v[2:3], v[2:3], v[186:187]
	v_cvt_pk_bf16_f32 v188, v4, v5
	v_cvt_pk_bf16_f32 v189, v6, v7
	v_cvt_pk_bf16_f32 v190, v0, v1
	v_cvt_pk_bf16_f32 v191, v2, v3
	v_cvt_pk_fp8_f32 v192, v4, v5
	v_cvt_pk_fp8_f32 v193, v0, v1
	v_cvt_pk_fp8_f32 v192, v6, v7 op_sel:[0,0,1]
	v_cvt_pk_fp8_f32 v193, v2, v3 op_sel:[0,0,1]
	v_add_u32_e32 v180, 0xb0000, v251
	v_add_u32_e32 v181, 0x58000, v252
	global_store_dwordx4 v180, v[188:191], s[68:69] offset:256
	global_store_dwordx2 v181, v[192:193], s[14:15] offset:128
	v_mul_f32_e32 v5, v5, v5
	v_mul_f32_e32 v7, v7, v7
	v_mul_f32_e32 v1, v1, v1
	v_mul_f32_e32 v3, v3, v3
	v_fmac_f32_e32 v5, v4, v4
	v_fmac_f32_e32 v7, v6, v6
	v_fmac_f32_e32 v1, v0, v0
	v_fmac_f32_e32 v3, v2, v2
	v_add_f32_e32 v5, v5, v7
	v_add_f32_e32 v5, v5, v1
	v_add_f32_e32 v5, v3, v5
	v_add_f32_e32 v249, v249, v5
	ds_bpermute_b32 v188, v254, v194
	ds_bpermute_b32 v189, v254, v195
	ds_bpermute_b32 v190, v254, v196
	ds_bpermute_b32 v191, v254, v249
	s_waitcnt lgkmcnt(0)
	v_add_f32_e32 v194, v194, v188
	v_add_f32_e32 v195, v195, v189
	v_add_f32_e32 v196, v196, v190
	v_add_f32_e32 v249, v249, v191
	ds_bpermute_b32 v188, v255, v194
	ds_bpermute_b32 v189, v255, v195
	ds_bpermute_b32 v190, v255, v196
	ds_bpermute_b32 v191, v255, v249
	s_waitcnt lgkmcnt(0)
	v_add_f32_e32 v194, v194, v188
	v_add_f32_e32 v195, v195, v189
	v_add_f32_e32 v196, v196, v190
	v_add_f32_e32 v249, v249, v191
	s_and_saveexec_b64 s[30:31], s[4:5]
	global_atomic_add_f32 v253, v194, s[12:13] offset:512
	global_atomic_add_f32 v253, v195, s[12:13] offset:576
	global_atomic_add_f32 v253, v196, s[12:13] offset:640
	global_atomic_add_f32 v253, v249, s[12:13] offset:704
	s_or_b64 exec, exec, s[30:31]
	s_andn2_b64 vcc, exec, s[6:7]
	s_mov_b64 s[6:7], -1
	s_cbranch_vccnz .LBB0_377
	s_andn2_b64 vcc, exec, s[10:11]
	s_cbranch_vccnz .LBB0_376
	s_barrier
	s_branch .LBB0_376

.LpgL0_group:
	v_mbcnt_lo_u32_b32 v249, -1, 0
	v_mbcnt_hi_u32_b32 v249, -1, v249
	v_and_b32_e32 v250, 15, v249
	v_lshrrev_b32_e32 v251, 4, v249
	v_and_b32_e32 v252, 3, v250
	v_cmp_eq_u32_e64 s[4:5], 1, v252
	v_cmp_eq_u32_e64 s[6:7], 2, v252
	v_cmp_eq_u32_e64 s[8:9], 3, v252
	v_cmp_eq_u32_e64 s[10:11], 0, v249
	s_add_u32 s12, s54, 0x29800000
	s_addc_u32 s13, s55, 0
	s_and_b32 s13, s13, 0xffff
	s_mov_b32 s14, 0x2000000
	s_mov_b32 s15, 0x20000
	s_add_u32 s16, s54, 0x8000000
	s_addc_u32 s17, s55, 0
	s_and_b32 s17, s17, 0xffff
	s_mov_b32 s18, 0x1000000
	s_mov_b32 s19, 0x20000
	s_add_u32 s20, s54, 0xc000000
	s_addc_u32 s21, s55, 0
	s_and_b32 s21, s21, 0xffff
	s_mov_b32 s22, 0x1000000
	s_mov_b32 s23, 0x20000
	s_add_u32 s30, s54, 0x80000
	s_addc_u32 s31, s55, 0
	s_add_u32 s34, s54, 0xc0000
	s_addc_u32 s35, s55, 0
	s_mov_b32 s94, 0xc3e00000
	s_mov_b32 s96, 0x800000
	s_mov_b32 s81, 0x1010101
	v_lshrrev_b32_e32 v253, 2, v250
	v_lshrrev_b32_e32 v254, 1, v251
	v_lshl_add_u32 v255, v253, 1, v254
	v_lshl_add_u32 v237, v255, 2, s91
	v_and_b32_e32 v255, 1, v251
	v_lshl_add_u32 v236, v255, 2, v252
	v_lshlrev_b32_e32 v236, 4, v236
	v_lshlrev_b32_e32 v254, 7, v254
	v_lshl_add_u32 v254, v252, 5, v254
	v_lshl_add_u32 v254, v255, 4, v254
	v_and_b32_e32 v253, 1, v253
	v_mov_b32_e32 v255, 0x7fff0000
	v_cmp_eq_u32_e32 vcc, 0, v253
	s_nop 1
	v_cndmask_b32_e32 v238, v255, v254, vcc
	v_cndmask_b32_e32 v239, v254, v255, vcc
	v_mov_b32_e32 v240, 0x7f7f7f7f
	v_mov_b32_e32 v255, 0x20202020
	v_cmp_gt_u32_e32 vcc, 8, v250
	s_nop 1
	v_cndmask_b32_e32 v241, v255, v240, vcc
	v_cndmask_b32_e32 v242, v240, v255, vcc
	v_lshrrev_b32_e32 v254, 3, v250
	v_lshl_add_u32 v254, v252, 1, v254
	v_lshl_add_u32 v255, v251, 1, v253
	v_lshl_add_u32 v244, v254, 3, v255
	v_lshlrev_b32_e32 v244, 2, v244
	v_add_u32_e32 v243, s91, v244
	v_and_b32_e32 v253, 3, v255
	v_lshrrev_b32_e32 v255, 2, v255
	v_lshl_add_u32 v253, v253, 1, v255
	v_lshl_add_u32 v253, v254, 3, v253
	v_lshlrev_b32_e32 v253, 2, v253
	v_add_u32_e32 v245, s91, v253
	v_add_u32_e32 v245, 0x1000, v245
	v_mov_b32_e32 v246, 0
	s_lshl_b32 s64, s63, 12
	s_add_u32 s24, s54, 0x28000000
	s_addc_u32 s25, s55, 0
	s_add_u32 s24, s24, s64
	s_addc_u32 s25, s25, 0
	s_lshl_b32 s64, s63, 12
	s_add_u32 s26, s54, 0x28800000
	s_addc_u32 s27, s55, 0
	s_add_u32 s26, s26, s64
	s_addc_u32 s27, s27, 0
	s_lshl_b32 s64, s63, 15
	s_add_u32 s28, s54, 0x18000000
	s_addc_u32 s29, s55, 0
	s_add_u32 s28, s28, s64
	s_addc_u32 s29, s29, 0
	s_lshl_b32 s64, s63, 5
	s_add_u32 s40, s54, 0x40000
	s_addc_u32 s41, s55, 0
	s_add_u32 s40, s40, s64
	s_addc_u32 s41, s41, 0
	s_lshl_b32 s64, s63, 5
	s_add_u32 s44, s54, 0x50000
	s_addc_u32 s45, s55, 0
	s_add_u32 s44, s44, s64
	s_addc_u32 s45, s45, 0
	s_lshl_b32 s61, s63, 14
	s_add_u32 s62, s61, 0x100
	v_mbcnt_lo_u32_b32 v253, -1, 0
	v_mbcnt_hi_u32_b32 v253, -1, v253
	v_lshlrev_b32_e32 v253, 2, v253
	global_load_dword v0, v253, s[24:25] offset:0
	global_load_dword v1, v253, s[24:25] offset:256
	global_load_dword v2, v253, s[24:25] offset:512
	global_load_dword v3, v253, s[24:25] offset:768
	global_load_dword v4, v253, s[24:25] offset:1024
	global_load_dword v5, v253, s[24:25] offset:1280
	global_load_dword v6, v253, s[24:25] offset:1536
	global_load_dword v7, v253, s[24:25] offset:1792
	global_load_dword v8, v253, s[24:25] offset:2048
	global_load_dword v9, v253, s[24:25] offset:2304
	global_load_dword v10, v253, s[24:25] offset:2560
	global_load_dword v11, v253, s[24:25] offset:2816
	global_load_dword v12, v253, s[24:25] offset:3072
	global_load_dword v13, v253, s[24:25] offset:3328
	global_load_dword v14, v253, s[24:25] offset:3584
	global_load_dword v15, v253, s[24:25] offset:3840
	v_add_u32_e32 v254, s91, v253
	s_waitcnt vmcnt(0)
	ds_write_b32 v254, v0 offset:0
	ds_write_b32 v254, v1 offset:256
	ds_write_b32 v254, v2 offset:512
	ds_write_b32 v254, v3 offset:768
	ds_write_b32 v254, v4 offset:1024
	ds_write_b32 v254, v5 offset:1280
	ds_write_b32 v254, v6 offset:1536
	ds_write_b32 v254, v7 offset:1792
	ds_write_b32 v254, v8 offset:2048
	ds_write_b32 v254, v9 offset:2304
	ds_write_b32 v254, v10 offset:2560
	ds_write_b32 v254, v11 offset:2816
	ds_write_b32 v254, v12 offset:3072
	ds_write_b32 v254, v13 offset:3328
	ds_write_b32 v254, v14 offset:3584
	ds_write_b32 v254, v15 offset:3840
	s_waitcnt lgkmcnt(0)
	s_lshl_b32 s61, s63, 14
	s_add_u32 s62, s61, 0x100
	v_mov_b32_e32 v204, 0
	v_mov_b32_e32 v205, 0
	v_mov_b32_e32 v206, 0
	v_mov_b32_e32 v207, 0
	v_mov_b32_e32 v208, 0
	v_mov_b32_e32 v209, 0
	v_mov_b32_e32 v210, 0
	v_mov_b32_e32 v211, 0
	v_mov_b32_e32 v212, 0
	v_mov_b32_e32 v213, 0
	v_mov_b32_e32 v214, 0
	v_mov_b32_e32 v215, 0
	v_mov_b32_e32 v216, 0
	v_mov_b32_e32 v217, 0
	v_mov_b32_e32 v218, 0
	v_mov_b32_e32 v219, 0
	v_mov_b32_e32 v176, 0
	v_mov_b32_e32 v177, 0
	v_mov_b32_e32 v178, 0
	v_mov_b32_e32 v179, 0
	v_mov_b32_e32 v180, 0
	v_mov_b32_e32 v181, 0
	v_mov_b32_e32 v182, 0
	v_mov_b32_e32 v183, 0
	v_mov_b32_e32 v184, 0
	v_mov_b32_e32 v185, 0
	v_mov_b32_e32 v186, 0
	v_mov_b32_e32 v187, 0
	v_mov_b32_e32 v188, 0
	v_mov_b32_e32 v189, 0
	v_mov_b32_e32 v190, 0
	v_mov_b32_e32 v191, 0
	s_mov_b32 s0, 0
	s_mov_b32 s1, 0
	s_mov_b32 s60, 0x200000
	ds_read_b32 v144, v237 offset:0
	ds_read_b32 v145, v237 offset:32
	ds_read_b32 v146, v237 offset:64
	ds_read_b32 v147, v237 offset:96
	ds_read_b32 v148, v237 offset:128
	ds_read_b32 v149, v237 offset:160
	ds_read_b32 v150, v237 offset:192
	ds_read_b32 v151, v237 offset:224
	s_waitcnt lgkmcnt(0)
	v_lshl_or_b32 v144, v144, 7, v236
	v_lshl_or_b32 v145, v145, 7, v236
	v_lshl_or_b32 v146, v146, 7, v236
	v_lshl_or_b32 v147, v147, 7, v236
	v_lshl_or_b32 v148, v148, 7, v236
	v_lshl_or_b32 v149, v149, 7, v236
	v_lshl_or_b32 v150, v150, 7, v236
	v_lshl_or_b32 v151, v151, 7, v236
	buffer_load_dwordx4 v[0:3], v144, s[16:19], s1 offen
	buffer_load_dwordx4 v[4:7], v145, s[16:19], s1 offen
	buffer_load_dwordx4 v[8:11], v146, s[16:19], s1 offen
	buffer_load_dwordx4 v[12:15], v147, s[16:19], s1 offen
	buffer_load_dwordx4 v[16:19], v148, s[16:19], s1 offen
	buffer_load_dwordx4 v[20:23], v149, s[16:19], s1 offen
	buffer_load_dwordx4 v[24:27], v150, s[16:19], s1 offen
	buffer_load_dwordx4 v[28:31], v151, s[16:19], s1 offen
	ds_read_b32 v144, v237 offset:256
	ds_read_b32 v145, v237 offset:288
	ds_read_b32 v146, v237 offset:320
	ds_read_b32 v147, v237 offset:352
	ds_read_b32 v148, v237 offset:384
	ds_read_b32 v149, v237 offset:416
	ds_read_b32 v150, v237 offset:448
	ds_read_b32 v151, v237 offset:480
	s_add_u32 s80, s61, 0x0
	buffer_load_dwordx4 v[128:131], v238, s[12:15], s80 offen
	buffer_load_dwordx4 v[132:135], v239, s[12:15], s80 offen
	s_waitcnt lgkmcnt(0)
	v_lshl_or_b32 v144, v144, 7, v236
	v_lshl_or_b32 v145, v145, 7, v236
	v_lshl_or_b32 v146, v146, 7, v236
	v_lshl_or_b32 v147, v147, 7, v236
	v_lshl_or_b32 v148, v148, 7, v236
	v_lshl_or_b32 v149, v149, 7, v236
	v_lshl_or_b32 v150, v150, 7, v236
	v_lshl_or_b32 v151, v151, 7, v236
	buffer_load_dwordx4 v[32:35], v144, s[16:19], s1 offen
	buffer_load_dwordx4 v[36:39], v145, s[16:19], s1 offen
	buffer_load_dwordx4 v[40:43], v146, s[16:19], s1 offen
	buffer_load_dwordx4 v[44:47], v147, s[16:19], s1 offen
	buffer_load_dwordx4 v[48:51], v148, s[16:19], s1 offen
	buffer_load_dwordx4 v[52:55], v149, s[16:19], s1 offen
	buffer_load_dwordx4 v[56:59], v150, s[16:19], s1 offen
	buffer_load_dwordx4 v[60:63], v151, s[16:19], s1 offen
	ds_read_b32 v144, v237 offset:512
	ds_read_b32 v145, v237 offset:544
	ds_read_b32 v146, v237 offset:576
	ds_read_b32 v147, v237 offset:608
	ds_read_b32 v148, v237 offset:640
	ds_read_b32 v149, v237 offset:672
	ds_read_b32 v150, v237 offset:704
	ds_read_b32 v151, v237 offset:736
	s_waitcnt lgkmcnt(0)
	v_lshl_or_b32 v144, v144, 7, v236
	v_lshl_or_b32 v145, v145, 7, v236
	v_lshl_or_b32 v146, v146, 7, v236
	v_lshl_or_b32 v147, v147, 7, v236
	v_lshl_or_b32 v148, v148, 7, v236
	v_lshl_or_b32 v149, v149, 7, v236
	v_lshl_or_b32 v150, v150, 7, v236
	v_lshl_or_b32 v151, v151, 7, v236
	buffer_load_dwordx4 v[64:67], v144, s[16:19], s1 offen
	buffer_load_dwordx4 v[68:71], v145, s[16:19], s1 offen
	buffer_load_dwordx4 v[72:75], v146, s[16:19], s1 offen
	buffer_load_dwordx4 v[76:79], v147, s[16:19], s1 offen
	buffer_load_dwordx4 v[80:83], v148, s[16:19], s1 offen
	buffer_load_dwordx4 v[84:87], v149, s[16:19], s1 offen
	buffer_load_dwordx4 v[88:91], v150, s[16:19], s1 offen
	buffer_load_dwordx4 v[92:95], v151, s[16:19], s1 offen
	ds_read_b32 v144, v237 offset:768
	ds_read_b32 v145, v237 offset:800
	ds_read_b32 v146, v237 offset:832
	ds_read_b32 v147, v237 offset:864
	ds_read_b32 v148, v237 offset:896
	ds_read_b32 v149, v237 offset:928
	ds_read_b32 v150, v237 offset:960
	ds_read_b32 v151, v237 offset:992

.LBB0_869:
	v_lshl_add_u32 v188, s30, 8, v129
	v_lshlrev_b32_e32 v253, 2, v188
	v_lshlrev_b32_e32 v188, 11, v188
	v_lshl_add_u32 v188, s28, 8, v188
	v_or_b32_e32 v252, v188, v128
	v_lshlrev_b32_e32 v251, 1, v252
	v_xor_b32_e32 v254, 16, v148
	v_xor_b32_e32 v255, 32, v148
	v_lshlrev_b32_e32 v254, 2, v254
	v_lshlrev_b32_e32 v255, 2, v255
	v_mov_b32_e32 v192, v251
	global_load_dwordx4 v[204:207], v192, s[68:69] offset:0
	global_load_dwordx4 v[208:211], v192, s[68:69] offset:256
	v_add_u32_e32 v192, 0x10000, v251
	global_load_dwordx4 v[212:215], v192, s[68:69] offset:0
	global_load_dwordx4 v[216:219], v192, s[68:69] offset:256
	v_add_u32_e32 v192, 0x20000, v251
	global_load_dwordx4 v[220:223], v192, s[68:69] offset:0
	global_load_dwordx4 v[224:227], v192, s[68:69] offset:256
	v_add_u32_e32 v192, 0x30000, v251
	global_load_dwordx4 v[228:231], v192, s[68:69] offset:0
	global_load_dwordx4 v[232:235], v192, s[68:69] offset:256
	v_add_u32_e32 v192, 0x80000, v251
	global_load_dwordx4 v[236:239], v192, s[68:69] offset:0
	global_load_dwordx4 v[240:243], v192, s[68:69] offset:256
	v_add_u32_e32 v192, 0x90000, v251
	global_load_dwordx4 v[244:247], v192, s[68:69] offset:0
	global_load_dwordx4 v[168:171], v192, s[68:69] offset:256
	v_add_u32_e32 v192, 0xa0000, v251
	global_load_dwordx4 v[172:175], v192, s[68:69] offset:0
	global_load_dwordx4 v[176:179], v192, s[68:69] offset:256
	v_add_u32_e32 v192, 0xb0000, v251
	global_load_dwordx4 v[180:183], v192, s[68:69] offset:0
	global_load_dwordx4 v[184:187], v192, s[68:69] offset:256
	s_waitcnt vmcnt(15)
	v_lshlrev_b32_e32 v188, 16, v204
	v_and_b32_e32 v189, 0xffff0000, v204
	v_pk_add_f32 v[124:125], v[124:125], v[188:189]
	v_lshlrev_b32_e32 v188, 16, v205
	v_and_b32_e32 v189, 0xffff0000, v205
	v_pk_add_f32 v[126:127], v[126:127], v[188:189]
	v_lshlrev_b32_e32 v188, 16, v206
	v_and_b32_e32 v189, 0xffff0000, v206
	v_pk_add_f32 v[120:121], v[120:121], v[188:189]
	v_lshlrev_b32_e32 v188, 16, v207
	v_and_b32_e32 v189, 0xffff0000, v207
	v_pk_add_f32 v[122:123], v[122:123], v[188:189]
	v_cvt_pk_bf16_f32 v188, v124, v125
	v_cvt_pk_bf16_f32 v189, v126, v127
	v_cvt_pk_bf16_f32 v190, v120, v121
	v_cvt_pk_bf16_f32 v191, v122, v123
	v_cvt_pk_fp8_f32 v192, v124, v125
	v_cvt_pk_fp8_f32 v193, v120, v121
	v_cvt_pk_fp8_f32 v192, v126, v127 op_sel:[0,0,1]
	v_cvt_pk_fp8_f32 v193, v122, v123 op_sel:[0,0,1]
	v_mov_b32_e32 v204, v251
	v_mov_b32_e32 v205, v252
	global_store_dwordx4 v204, v[188:191], s[68:69] offset:0
	global_store_dwordx2 v205, v[192:193], s[14:15] offset:0
	v_mul_f32_e32 v125, v125, v125
	v_mul_f32_e32 v127, v127, v127
	v_mul_f32_e32 v121, v121, v121
	v_mul_f32_e32 v123, v123, v123
	v_fmac_f32_e32 v125, v124, v124
	v_fmac_f32_e32 v127, v126, v126
	v_fmac_f32_e32 v121, v120, v120
	v_fmac_f32_e32 v123, v122, v122
	v_add_f32_e32 v125, v125, v127
	v_add_f32_e32 v125, v125, v121
	v_add_f32_e32 v194, v123, v125
	s_waitcnt vmcnt(16)
	v_lshlrev_b32_e32 v188, 16, v208
	v_and_b32_e32 v189, 0xffff0000, v208
	v_pk_add_f32 v[116:117], v[116:117], v[188:189]
	v_lshlrev_b32_e32 v188, 16, v209
	v_and_b32_e32 v189, 0xffff0000, v209
	v_pk_add_f32 v[118:119], v[118:119], v[188:189]
	v_lshlrev_b32_e32 v188, 16, v210
	v_and_b32_e32 v189, 0xffff0000, v210
	v_pk_add_f32 v[112:113], v[112:113], v[188:189]
	v_lshlrev_b32_e32 v188, 16, v211
	v_and_b32_e32 v189, 0xffff0000, v211
	v_pk_add_f32 v[114:115], v[114:115], v[188:189]
	v_cvt_pk_bf16_f32 v188, v116, v117
	v_cvt_pk_bf16_f32 v189, v118, v119
	v_cvt_pk_bf16_f32 v190, v112, v113
	v_cvt_pk_bf16_f32 v191, v114, v115
	v_cvt_pk_fp8_f32 v192, v116, v117
	v_cvt_pk_fp8_f32 v193, v112, v113
	v_cvt_pk_fp8_f32 v192, v118, v119 op_sel:[0,0,1]
	v_cvt_pk_fp8_f32 v193, v114, v115 op_sel:[0,0,1]
	v_mov_b32_e32 v208, v251
	v_mov_b32_e32 v209, v252
	global_store_dwordx4 v208, v[188:191], s[68:69] offset:256
	global_store_dwordx2 v209, v[192:193], s[14:15] offset:128
	v_mul_f32_e32 v117, v117, v117
	v_mul_f32_e32 v119, v119, v119
	v_mul_f32_e32 v113, v113, v113
	v_mul_f32_e32 v115, v115, v115
	v_fmac_f32_e32 v117, v116, v116
	v_fmac_f32_e32 v119, v118, v118
	v_fmac_f32_e32 v113, v112, v112
	v_fmac_f32_e32 v115, v114, v114
	v_add_f32_e32 v117, v117, v119
	v_add_f32_e32 v117, v117, v113
	v_add_f32_e32 v117, v115, v117
	v_add_f32_e32 v194, v194, v117
	s_waitcnt vmcnt(17)
	v_lshlrev_b32_e32 v188, 16, v212
	v_and_b32_e32 v189, 0xffff0000, v212
	v_pk_add_f32 v[108:109], v[108:109], v[188:189]
	v_lshlrev_b32_e32 v188, 16, v213
	v_and_b32_e32 v189, 0xffff0000, v213
	v_pk_add_f32 v[110:111], v[110:111], v[188:189]
	v_lshlrev_b32_e32 v188, 16, v214
	v_and_b32_e32 v189, 0xffff0000, v214
	v_pk_add_f32 v[104:105], v[104:105], v[188:189]
	v_lshlrev_b32_e32 v188, 16, v215
	v_and_b32_e32 v189, 0xffff0000, v215
	v_pk_add_f32 v[106:107], v[106:107], v[188:189]
	v_cvt_pk_bf16_f32 v188, v108, v109
	v_cvt_pk_bf16_f32 v189, v110, v111
	v_cvt_pk_bf16_f32 v190, v104, v105
	v_cvt_pk_bf16_f32 v191, v106, v107
	v_cvt_pk_fp8_f32 v192, v108, v109
	v_cvt_pk_fp8_f32 v193, v104, v105
	v_cvt_pk_fp8_f32 v192, v110, v111 op_sel:[0,0,1]
	v_cvt_pk_fp8_f32 v193, v106, v107 op_sel:[0,0,1]
	v_add_u32_e32 v212, 0x10000, v251
	v_add_u32_e32 v213, 0x8000, v252
	global_store_dwordx4 v212, v[188:191], s[68:69] offset:0
	global_store_dwordx2 v213, v[192:193], s[14:15] offset:0
	v_mul_f32_e32 v109, v109, v109
	v_mul_f32_e32 v111, v111, v111
	v_mul_f32_e32 v105, v105, v105
	v_mul_f32_e32 v107, v107, v107
	v_fmac_f32_e32 v109, v108, v108
	v_fmac_f32_e32 v111, v110, v110
	v_fmac_f32_e32 v105, v104, v104
	v_fmac_f32_e32 v107, v106, v106
	v_add_f32_e32 v109, v109, v111
	v_add_f32_e32 v109, v109, v105
	v_add_f32_e32 v195, v107, v109
	s_waitcnt vmcnt(18)
	v_lshlrev_b32_e32 v188, 16, v216
	v_and_b32_e32 v189, 0xffff0000, v216
	v_pk_add_f32 v[100:101], v[100:101], v[188:189]
	v_lshlrev_b32_e32 v188, 16, v217
	v_and_b32_e32 v189, 0xffff0000, v217
	v_pk_add_f32 v[102:103], v[102:103], v[188:189]
	v_lshlrev_b32_e32 v188, 16, v218
	v_and_b32_e32 v189, 0xffff0000, v218
	v_pk_add_f32 v[96:97], v[96:97], v[188:189]
	v_lshlrev_b32_e32 v188, 16, v219
	v_and_b32_e32 v189, 0xffff0000, v219
	v_pk_add_f32 v[98:99], v[98:99], v[188:189]
	v_cvt_pk_bf16_f32 v188, v100, v101
	v_cvt_pk_bf16_f32 v189, v102, v103
	v_cvt_pk_bf16_f32 v190, v96, v97
	v_cvt_pk_bf16_f32 v191, v98, v99
	v_cvt_pk_fp8_f32 v192, v100, v101
	v_cvt_pk_fp8_f32 v193, v96, v97
	v_cvt_pk_fp8_f32 v192, v102, v103 op_sel:[0,0,1]
	v_cvt_pk_fp8_f32 v193, v98, v99 op_sel:[0,0,1]
	v_add_u32_e32 v216, 0x10000, v251
	v_add_u32_e32 v217, 0x8000, v252
	global_store_dwordx4 v216, v[188:191], s[68:69] offset:256
	global_store_dwordx2 v217, v[192:193], s[14:15] offset:128
	v_mul_f32_e32 v101, v101, v101
	v_mul_f32_e32 v103, v103, v103
	v_mul_f32_e32 v97, v97, v97
	v_mul_f32_e32 v99, v99, v99
	v_fmac_f32_e32 v101, v100, v100
	v_fmac_f32_e32 v103, v102, v102
	v_fmac_f32_e32 v97, v96, v96
	v_fmac_f32_e32 v99, v98, v98
	v_add_f32_e32 v101, v101, v103
	v_add_f32_e32 v101, v101, v97
	v_add_f32_e32 v101, v99, v101
	v_add_f32_e32 v195, v195, v101
	s_waitcnt vmcnt(19)
	v_lshlrev_b32_e32 v188, 16, v220
	v_and_b32_e32 v189, 0xffff0000, v220
	v_pk_add_f32 v[92:93], v[92:93], v[188:189]
	v_lshlrev_b32_e32 v188, 16, v221
	v_and_b32_e32 v189, 0xffff0000, v221
	v_pk_add_f32 v[94:95], v[94:95], v[188:189]
	v_lshlrev_b32_e32 v188, 16, v222
	v_and_b32_e32 v189, 0xffff0000, v222
	v_pk_add_f32 v[88:89], v[88:89], v[188:189]
	v_lshlrev_b32_e32 v188, 16, v223
	v_and_b32_e32 v189, 0xffff0000, v223
	v_pk_add_f32 v[90:91], v[90:91], v[188:189]
	v_cvt_pk_bf16_f32 v188, v92, v93
	v_cvt_pk_bf16_f32 v189, v94, v95
	v_cvt_pk_bf16_f32 v190, v88, v89
	v_cvt_pk_bf16_f32 v191, v90, v91
	v_cvt_pk_fp8_f32 v192, v92, v93
	v_cvt_pk_fp8_f32 v193, v88, v89
	v_cvt_pk_fp8_f32 v192, v94, v95 op_sel:[0,0,1]
	v_cvt_pk_fp8_f32 v193, v90, v91 op_sel:[0,0,1]
	v_add_u32_e32 v220, 0x20000, v251
	v_add_u32_e32 v221, 0x10000, v252
	global_store_dwordx4 v220, v[188:191], s[68:69] offset:0
	global_store_dwordx2 v221, v[192:193], s[14:15] offset:0
	v_mul_f32_e32 v93, v93, v93
	v_mul_f32_e32 v95, v95, v95
	v_mul_f32_e32 v89, v89, v89
	v_mul_f32_e32 v91, v91, v91
	v_fmac_f32_e32 v93, v92, v92
	v_fmac_f32_e32 v95, v94, v94
	v_fmac_f32_e32 v89, v88, v88
	v_fmac_f32_e32 v91, v90, v90
	v_add_f32_e32 v93, v93, v95
	v_add_f32_e32 v93, v93, v89
	v_add_f32_e32 v196, v91, v93
	s_waitcnt vmcnt(20)
	v_lshlrev_b32_e32 v188, 16, v224
	v_and_b32_e32 v189, 0xffff0000, v224
	v_pk_add_f32 v[84:85], v[84:85], v[188:189]
	v_lshlrev_b32_e32 v188, 16, v225
	v_and_b32_e32 v189, 0xffff0000, v225
	v_pk_add_f32 v[86:87], v[86:87], v[188:189]
	v_lshlrev_b32_e32 v188, 16, v226
	v_and_b32_e32 v189, 0xffff0000, v226
	v_pk_add_f32 v[80:81], v[80:81], v[188:189]
	v_lshlrev_b32_e32 v188, 16, v227
	v_and_b32_e32 v189, 0xffff0000, v227
	v_pk_add_f32 v[82:83], v[82:83], v[188:189]
	v_cvt_pk_bf16_f32 v188, v84, v85
	v_cvt_pk_bf16_f32 v189, v86, v87
	v_cvt_pk_bf16_f32 v190, v80, v81
	v_cvt_pk_bf16_f32 v191, v82, v83
	v_cvt_pk_fp8_f32 v192, v84, v85
	v_cvt_pk_fp8_f32 v193, v80, v81
	v_cvt_pk_fp8_f32 v192, v86, v87 op_sel:[0,0,1]
	v_cvt_pk_fp8_f32 v193, v82, v83 op_sel:[0,0,1]
	v_add_u32_e32 v224, 0x20000, v251
	v_add_u32_e32 v225, 0x10000, v252
	global_store_dwordx4 v224, v[188:191], s[68:69] offset:256
	global_store_dwordx2 v225, v[192:193], s[14:15] offset:128
	v_mul_f32_e32 v85, v85, v85
	v_mul_f32_e32 v87, v87, v87
	v_mul_f32_e32 v81, v81, v81
	v_mul_f32_e32 v83, v83, v83
	v_fmac_f32_e32 v85, v84, v84
	v_fmac_f32_e32 v87, v86, v86
	v_fmac_f32_e32 v81, v80, v80
	v_fmac_f32_e32 v83, v82, v82
	v_add_f32_e32 v85, v85, v87
	v_add_f32_e32 v85, v85, v81
	v_add_f32_e32 v85, v83, v85
	v_add_f32_e32 v196, v196, v85
	s_waitcnt vmcnt(21)
	v_lshlrev_b32_e32 v188, 16, v228
	v_and_b32_e32 v189, 0xffff0000, v228
	v_pk_add_f32 v[76:77], v[76:77], v[188:189]
	v_lshlrev_b32_e32 v188, 16, v229
	v_and_b32_e32 v189, 0xffff0000, v229
	v_pk_add_f32 v[78:79], v[78:79], v[188:189]
	v_lshlrev_b32_e32 v188, 16, v230
	v_and_b32_e32 v189, 0xffff0000, v230
	v_pk_add_f32 v[72:73], v[72:73], v[188:189]
	v_lshlrev_b32_e32 v188, 16, v231
	v_and_b32_e32 v189, 0xffff0000, v231
	v_pk_add_f32 v[74:75], v[74:75], v[188:189]
	v_cvt_pk_bf16_f32 v188, v76, v77
	v_cvt_pk_bf16_f32 v189, v78, v79
	v_cvt_pk_bf16_f32 v190, v72, v73
	v_cvt_pk_bf16_f32 v191, v74, v75
	v_cvt_pk_fp8_f32 v192, v76, v77
	v_cvt_pk_fp8_f32 v193, v72, v73
	v_cvt_pk_fp8_f32 v192, v78, v79 op_sel:[0,0,1]
	v_cvt_pk_fp8_f32 v193, v74, v75 op_sel:[0,0,1]
	v_add_u32_e32 v228, 0x30000, v251
	v_add_u32_e32 v229, 0x18000, v252
	global_store_dwordx4 v228, v[188:191], s[68:69] offset:0
	global_store_dwordx2 v229, v[192:193], s[14:15] offset:0
	v_mul_f32_e32 v77, v77, v77
	v_mul_f32_e32 v79, v79, v79
	v_mul_f32_e32 v73, v73, v73
	v_mul_f32_e32 v75, v75, v75
	v_fmac_f32_e32 v77, v76, v76
	v_fmac_f32_e32 v79, v78, v78
	v_fmac_f32_e32 v73, v72, v72
	v_fmac_f32_e32 v75, v74, v74
	v_add_f32_e32 v77, v77, v79
	v_add_f32_e32 v77, v77, v73
	v_add_f32_e32 v249, v75, v77
	s_waitcnt vmcnt(22)
	v_lshlrev_b32_e32 v188, 16, v232
	v_and_b32_e32 v189, 0xffff0000, v232
	v_pk_add_f32 v[68:69], v[68:69], v[188:189]
	v_lshlrev_b32_e32 v188, 16, v233
	v_and_b32_e32 v189, 0xffff0000, v233
	v_pk_add_f32 v[70:71], v[70:71], v[188:189]
	v_lshlrev_b32_e32 v188, 16, v234
	v_and_b32_e32 v189, 0xffff0000, v234
	v_pk_add_f32 v[64:65], v[64:65], v[188:189]
	v_lshlrev_b32_e32 v188, 16, v235
	v_and_b32_e32 v189, 0xffff0000, v235
	v_pk_add_f32 v[66:67], v[66:67], v[188:189]
	v_cvt_pk_bf16_f32 v188, v68, v69
	v_cvt_pk_bf16_f32 v189, v70, v71
	v_cvt_pk_bf16_f32 v190, v64, v65
	v_cvt_pk_bf16_f32 v191, v66, v67
	v_cvt_pk_fp8_f32 v192, v68, v69
	v_cvt_pk_fp8_f32 v193, v64, v65
	v_cvt_pk_fp8_f32 v192, v70, v71 op_sel:[0,0,1]
	v_cvt_pk_fp8_f32 v193, v66, v67 op_sel:[0,0,1]
	v_add_u32_e32 v232, 0x30000, v251
	v_add_u32_e32 v233, 0x18000, v252
	global_store_dwordx4 v232, v[188:191], s[68:69] offset:256
	global_store_dwordx2 v233, v[192:193], s[14:15] offset:128
	v_mul_f32_e32 v69, v69, v69
	v_mul_f32_e32 v71, v71, v71
	v_mul_f32_e32 v65, v65, v65
	v_mul_f32_e32 v67, v67, v67
	v_fmac_f32_e32 v69, v68, v68
	v_fmac_f32_e32 v71, v70, v70
	v_fmac_f32_e32 v65, v64, v64
	v_fmac_f32_e32 v67, v66, v66
	v_add_f32_e32 v69, v69, v71
	v_add_f32_e32 v69, v69, v65
	v_add_f32_e32 v69, v67, v69
	v_add_f32_e32 v249, v249, v69
	ds_bpermute_b32 v188, v254, v194
	ds_bpermute_b32 v189, v254, v195
	ds_bpermute_b32 v190, v254, v196
	ds_bpermute_b32 v191, v254, v249
	s_waitcnt lgkmcnt(0)
	v_add_f32_e32 v194, v194, v188
	v_add_f32_e32 v195, v195, v189
	v_add_f32_e32 v196, v196, v190
	v_add_f32_e32 v249, v249, v191
	ds_bpermute_b32 v188, v255, v194
	ds_bpermute_b32 v189, v255, v195
	ds_bpermute_b32 v190, v255, v196
	ds_bpermute_b32 v191, v255, v249
	s_waitcnt lgkmcnt(0)
	v_add_f32_e32 v194, v194, v188
	v_add_f32_e32 v195, v195, v189
	v_add_f32_e32 v196, v196, v190
	v_add_f32_e32 v249, v249, v191
	s_and_saveexec_b64 s[28:29], s[4:5]
	global_atomic_add_f32 v253, v194, s[12:13] offset:0
	global_atomic_add_f32 v253, v195, s[12:13] offset:64
	global_atomic_add_f32 v253, v196, s[12:13] offset:128
	global_atomic_add_f32 v253, v249, s[12:13] offset:192
	s_or_b64 exec, exec, s[28:29]
	s_waitcnt vmcnt(27)
	v_lshlrev_b32_e32 v188, 16, v236
	v_and_b32_e32 v189, 0xffff0000, v236
	v_pk_add_f32 v[60:61], v[60:61], v[188:189]
	v_lshlrev_b32_e32 v188, 16, v237
	v_and_b32_e32 v189, 0xffff0000, v237
	v_pk_add_f32 v[62:63], v[62:63], v[188:189]
	v_lshlrev_b32_e32 v188, 16, v238
	v_and_b32_e32 v189, 0xffff0000, v238
	v_pk_add_f32 v[56:57], v[56:57], v[188:189]
	v_lshlrev_b32_e32 v188, 16, v239
	v_and_b32_e32 v189, 0xffff0000, v239
	v_pk_add_f32 v[58:59], v[58:59], v[188:189]
	v_cvt_pk_bf16_f32 v188, v60, v61
	v_cvt_pk_bf16_f32 v189, v62, v63
	v_cvt_pk_bf16_f32 v190, v56, v57
	v_cvt_pk_bf16_f32 v191, v58, v59
	v_cvt_pk_fp8_f32 v192, v60, v61
	v_cvt_pk_fp8_f32 v193, v56, v57
	v_cvt_pk_fp8_f32 v192, v62, v63 op_sel:[0,0,1]
	v_cvt_pk_fp8_f32 v193, v58, v59 op_sel:[0,0,1]
	v_add_u32_e32 v236, 0x80000, v251
	v_add_u32_e32 v237, 0x40000, v252
	global_store_dwordx4 v236, v[188:191], s[68:69] offset:0
	global_store_dwordx2 v237, v[192:193], s[14:15] offset:0
	v_mul_f32_e32 v61, v61, v61
	v_mul_f32_e32 v63, v63, v63
	v_mul_f32_e32 v57, v57, v57
	v_mul_f32_e32 v59, v59, v59
	v_fmac_f32_e32 v61, v60, v60
	v_fmac_f32_e32 v63, v62, v62
	v_fmac_f32_e32 v57, v56, v56
	v_fmac_f32_e32 v59, v58, v58
	v_add_f32_e32 v61, v61, v63
	v_add_f32_e32 v61, v61, v57
	v_add_f32_e32 v194, v59, v61
	s_waitcnt vmcnt(28)
	v_lshlrev_b32_e32 v188, 16, v240
	v_and_b32_e32 v189, 0xffff0000, v240
	v_pk_add_f32 v[52:53], v[52:53], v[188:189]
	v_lshlrev_b32_e32 v188, 16, v241
	v_and_b32_e32 v189, 0xffff0000, v241
	v_pk_add_f32 v[54:55], v[54:55], v[188:189]
	v_lshlrev_b32_e32 v188, 16, v242
	v_and_b32_e32 v189, 0xffff0000, v242
	v_pk_add_f32 v[48:49], v[48:49], v[188:189]
	v_lshlrev_b32_e32 v188, 16, v243
	v_and_b32_e32 v189, 0xffff0000, v243
	v_pk_add_f32 v[50:51], v[50:51], v[188:189]
	v_cvt_pk_bf16_f32 v188, v52, v53
	v_cvt_pk_bf16_f32 v189, v54, v55
	v_cvt_pk_bf16_f32 v190, v48, v49
	v_cvt_pk_bf16_f32 v191, v50, v51
	v_cvt_pk_fp8_f32 v192, v52, v53
	v_cvt_pk_fp8_f32 v193, v48, v49
	v_cvt_pk_fp8_f32 v192, v54, v55 op_sel:[0,0,1]
	v_cvt_pk_fp8_f32 v193, v50, v51 op_sel:[0,0,1]
	v_add_u32_e32 v240, 0x80000, v251
	v_add_u32_e32 v241, 0x40000, v252
	global_store_dwordx4 v240, v[188:191], s[68:69] offset:256
	global_store_dwordx2 v241, v[192:193], s[14:15] offset:128
	v_mul_f32_e32 v53, v53, v53
	v_mul_f32_e32 v55, v55, v55
	v_mul_f32_e32 v49, v49, v49
	v_mul_f32_e32 v51, v51, v51
	v_fmac_f32_e32 v53, v52, v52
	v_fmac_f32_e32 v55, v54, v54
	v_fmac_f32_e32 v49, v48, v48
	v_fmac_f32_e32 v51, v50, v50
	v_add_f32_e32 v53, v53, v55
	v_add_f32_e32 v53, v53, v49
	v_add_f32_e32 v53, v51, v53
	v_add_f32_e32 v194, v194, v53
	s_waitcnt vmcnt(29)
	v_lshlrev_b32_e32 v188, 16, v244
	v_and_b32_e32 v189, 0xffff0000, v244
	v_pk_add_f32 v[44:45], v[44:45], v[188:189]
	v_lshlrev_b32_e32 v188, 16, v245
	v_and_b32_e32 v189, 0xffff0000, v245
	v_pk_add_f32 v[46:47], v[46:47], v[188:189]
	v_lshlrev_b32_e32 v188, 16, v246
	v_and_b32_e32 v189, 0xffff0000, v246
	v_pk_add_f32 v[40:41], v[40:41], v[188:189]
	v_lshlrev_b32_e32 v188, 16, v247
	v_and_b32_e32 v189, 0xffff0000, v247
	v_pk_add_f32 v[42:43], v[42:43], v[188:189]
	v_cvt_pk_bf16_f32 v188, v44, v45
	v_cvt_pk_bf16_f32 v189, v46, v47
	v_cvt_pk_bf16_f32 v190, v40, v41
	v_cvt_pk_bf16_f32 v191, v42, v43
	v_cvt_pk_fp8_f32 v192, v44, v45
	v_cvt_pk_fp8_f32 v193, v40, v41
	v_cvt_pk_fp8_f32 v192, v46, v47 op_sel:[0,0,1]
	v_cvt_pk_fp8_f32 v193, v42, v43 op_sel:[0,0,1]
	v_add_u32_e32 v244, 0x90000, v251
	v_add_u32_e32 v245, 0x48000, v252
	global_store_dwordx4 v244, v[188:191], s[68:69] offset:0
	global_store_dwordx2 v245, v[192:193], s[14:15] offset:0
	v_mul_f32_e32 v45, v45, v45
	v_mul_f32_e32 v47, v47, v47
	v_mul_f32_e32 v41, v41, v41
	v_mul_f32_e32 v43, v43, v43
	v_fmac_f32_e32 v45, v44, v44
	v_fmac_f32_e32 v47, v46, v46
	v_fmac_f32_e32 v41, v40, v40
	v_fmac_f32_e32 v43, v42, v42
	v_add_f32_e32 v45, v45, v47
	v_add_f32_e32 v45, v45, v41
	v_add_f32_e32 v195, v43, v45
	s_waitcnt vmcnt(30)
	v_lshlrev_b32_e32 v188, 16, v168
	v_and_b32_e32 v189, 0xffff0000, v168
	v_pk_add_f32 v[36:37], v[36:37], v[188:189]
	v_lshlrev_b32_e32 v188, 16, v169
	v_and_b32_e32 v189, 0xffff0000, v169
	v_pk_add_f32 v[38:39], v[38:39], v[188:189]
	v_lshlrev_b32_e32 v188, 16, v170
	v_and_b32_e32 v189, 0xffff0000, v170
	v_pk_add_f32 v[32:33], v[32:33], v[188:189]
	v_lshlrev_b32_e32 v188, 16, v171
	v_and_b32_e32 v189, 0xffff0000, v171
	v_pk_add_f32 v[34:35], v[34:35], v[188:189]
	v_cvt_pk_bf16_f32 v188, v36, v37
	v_cvt_pk_bf16_f32 v189, v38, v39
	v_cvt_pk_bf16_f32 v190, v32, v33
	v_cvt_pk_bf16_f32 v191, v34, v35
	v_cvt_pk_fp8_f32 v192, v36, v37
	v_cvt_pk_fp8_f32 v193, v32, v33
	v_cvt_pk_fp8_f32 v192, v38, v39 op_sel:[0,0,1]
	v_cvt_pk_fp8_f32 v193, v34, v35 op_sel:[0,0,1]
	v_add_u32_e32 v168, 0x90000, v251
	v_add_u32_e32 v169, 0x48000, v252
	global_store_dwordx4 v168, v[188:191], s[68:69] offset:256
	global_store_dwordx2 v169, v[192:193], s[14:15] offset:128
	v_mul_f32_e32 v37, v37, v37
	v_mul_f32_e32 v39, v39, v39
	v_mul_f32_e32 v33, v33, v33
	v_mul_f32_e32 v35, v35, v35
	v_fmac_f32_e32 v37, v36, v36
	v_fmac_f32_e32 v39, v38, v38
	v_fmac_f32_e32 v33, v32, v32
	v_fmac_f32_e32 v35, v34, v34
	v_add_f32_e32 v37, v37, v39
	v_add_f32_e32 v37, v37, v33
	v_add_f32_e32 v37, v35, v37
	v_add_f32_e32 v195, v195, v37
	s_waitcnt vmcnt(31)
	v_lshlrev_b32_e32 v188, 16, v172
	v_and_b32_e32 v189, 0xffff0000, v172
	v_pk_add_f32 v[28:29], v[28:29], v[188:189]
	v_lshlrev_b32_e32 v188, 16, v173
	v_and_b32_e32 v189, 0xffff0000, v173
	v_pk_add_f32 v[30:31], v[30:31], v[188:189]
	v_lshlrev_b32_e32 v188, 16, v174
	v_and_b32_e32 v189, 0xffff0000, v174
	v_pk_add_f32 v[24:25], v[24:25], v[188:189]
	v_lshlrev_b32_e32 v188, 16, v175
	v_and_b32_e32 v189, 0xffff0000, v175
	v_pk_add_f32 v[26:27], v[26:27], v[188:189]
	v_cvt_pk_bf16_f32 v188, v28, v29
	v_cvt_pk_bf16_f32 v189, v30, v31
	v_cvt_pk_bf16_f32 v190, v24, v25
	v_cvt_pk_bf16_f32 v191, v26, v27
	v_cvt_pk_fp8_f32 v192, v28, v29
	v_cvt_pk_fp8_f32 v193, v24, v25
	v_cvt_pk_fp8_f32 v192, v30, v31 op_sel:[0,0,1]
	v_cvt_pk_fp8_f32 v193, v26, v27 op_sel:[0,0,1]
	v_add_u32_e32 v172, 0xa0000, v251
	v_add_u32_e32 v173, 0x50000, v252
	global_store_dwordx4 v172, v[188:191], s[68:69] offset:0
	global_store_dwordx2 v173, v[192:193], s[14:15] offset:0
	v_mul_f32_e32 v29, v29, v29
	v_mul_f32_e32 v31, v31, v31
	v_mul_f32_e32 v25, v25, v25
	v_mul_f32_e32 v27, v27, v27
	v_fmac_f32_e32 v29, v28, v28
	v_fmac_f32_e32 v31, v30, v30
	v_fmac_f32_e32 v25, v24, v24
	v_fmac_f32_e32 v27, v26, v26
	v_add_f32_e32 v29, v29, v31
	v_add_f32_e32 v29, v29, v25
	v_add_f32_e32 v196, v27, v29
	s_waitcnt vmcnt(32)
	v_lshlrev_b32_e32 v188, 16, v176
	v_and_b32_e32 v189, 0xffff0000, v176
	v_pk_add_f32 v[20:21], v[20:21], v[188:189]
	v_lshlrev_b32_e32 v188, 16, v177
	v_and_b32_e32 v189, 0xffff0000, v177
	v_pk_add_f32 v[22:23], v[22:23], v[188:189]
	v_lshlrev_b32_e32 v188, 16, v178
	v_and_b32_e32 v189, 0xffff0000, v178
	v_pk_add_f32 v[16:17], v[16:17], v[188:189]
	v_lshlrev_b32_e32 v188, 16, v179
	v_and_b32_e32 v189, 0xffff0000, v179
	v_pk_add_f32 v[18:19], v[18:19], v[188:189]
	v_cvt_pk_bf16_f32 v188, v20, v21
	v_cvt_pk_bf16_f32 v189, v22, v23
	v_cvt_pk_bf16_f32 v190, v16, v17
	v_cvt_pk_bf16_f32 v191, v18, v19
	v_cvt_pk_fp8_f32 v192, v20, v21
	v_cvt_pk_fp8_f32 v193, v16, v17
	v_cvt_pk_fp8_f32 v192, v22, v23 op_sel:[0,0,1]
	v_cvt_pk_fp8_f32 v193, v18, v19 op_sel:[0,0,1]
	v_add_u32_e32 v176, 0xa0000, v251
	v_add_u32_e32 v177, 0x50000, v252
	global_store_dwordx4 v176, v[188:191], s[68:69] offset:256
	global_store_dwordx2 v177, v[192:193], s[14:15] offset:128
	v_mul_f32_e32 v21, v21, v21
	v_mul_f32_e32 v23, v23, v23
	v_mul_f32_e32 v17, v17, v17
	v_mul_f32_e32 v19, v19, v19
	v_fmac_f32_e32 v21, v20, v20
	v_fmac_f32_e32 v23, v22, v22
	v_fmac_f32_e32 v17, v16, v16
	v_fmac_f32_e32 v19, v18, v18
	v_add_f32_e32 v21, v21, v23
	v_add_f32_e32 v21, v21, v17
	v_add_f32_e32 v21, v19, v21
	v_add_f32_e32 v196, v196, v21
	s_waitcnt vmcnt(33)
	v_lshlrev_b32_e32 v188, 16, v180
	v_and_b32_e32 v189, 0xffff0000, v180
	v_pk_add_f32 v[12:13], v[12:13], v[188:189]
	v_lshlrev_b32_e32 v188, 16, v181
	v_and_b32_e32 v189, 0xffff0000, v181
	v_pk_add_f32 v[14:15], v[14:15], v[188:189]
	v_lshlrev_b32_e32 v188, 16, v182
	v_and_b32_e32 v189, 0xffff0000, v182
	v_pk_add_f32 v[8:9], v[8:9], v[188:189]
	v_lshlrev_b32_e32 v188, 16, v183
	v_and_b32_e32 v189, 0xffff0000, v183
	v_pk_add_f32 v[10:11], v[10:11], v[188:189]
	v_cvt_pk_bf16_f32 v188, v12, v13
	v_cvt_pk_bf16_f32 v189, v14, v15
	v_cvt_pk_bf16_f32 v190, v8, v9
	v_cvt_pk_bf16_f32 v191, v10, v11
	v_cvt_pk_fp8_f32 v192, v12, v13
	v_cvt_pk_fp8_f32 v193, v8, v9
	v_cvt_pk_fp8_f32 v192, v14, v15 op_sel:[0,0,1]
	v_cvt_pk_fp8_f32 v193, v10, v11 op_sel:[0,0,1]
	v_add_u32_e32 v180, 0xb0000, v251
	v_add_u32_e32 v181, 0x58000, v252
	global_store_dwordx4 v180, v[188:191], s[68:69] offset:0
	global_store_dwordx2 v181, v[192:193], s[14:15] offset:0
	v_mul_f32_e32 v13, v13, v13
	v_mul_f32_e32 v15, v15, v15
	v_mul_f32_e32 v9, v9, v9
	v_mul_f32_e32 v11, v11, v11
	v_fmac_f32_e32 v13, v12, v12
	v_fmac_f32_e32 v15, v14, v14
	v_fmac_f32_e32 v9, v8, v8
	v_fmac_f32_e32 v11, v10, v10
	v_add_f32_e32 v13, v13, v15
	v_add_f32_e32 v13, v13, v9
	v_add_f32_e32 v249, v11, v13
	s_waitcnt vmcnt(34)
	v_lshlrev_b32_e32 v188, 16, v184
	v_and_b32_e32 v189, 0xffff0000, v184
	v_pk_add_f32 v[4:5], v[4:5], v[188:189]
	v_lshlrev_b32_e32 v188, 16, v185
	v_and_b32_e32 v189, 0xffff0000, v185
	v_pk_add_f32 v[6:7], v[6:7], v[188:189]
	v_lshlrev_b32_e32 v188, 16, v186
	v_and_b32_e32 v189, 0xffff0000, v186
	v_pk_add_f32 v[0:1], v[0:1], v[188:189]
	v_lshlrev_b32_e32 v188, 16, v187
	v_and_b32_e32 v189, 0xffff0000, v187
	v_pk_add_f32 v[2:3], v[2:3], v[188:189]
	v_cvt_pk_bf16_f32 v188, v4, v5
	v_cvt_pk_bf16_f32 v189, v6, v7
	v_cvt_pk_bf16_f32 v190, v0, v1
	v_cvt_pk_bf16_f32 v191, v2, v3
	v_cvt_pk_fp8_f32 v192, v4, v5
	v_cvt_pk_fp8_f32 v193, v0, v1
	v_cvt_pk_fp8_f32 v192, v6, v7 op_sel:[0,0,1]
	v_cvt_pk_fp8_f32 v193, v2, v3 op_sel:[0,0,1]
	v_add_u32_e32 v184, 0xb0000, v251
	v_add_u32_e32 v185, 0x58000, v252
	global_store_dwordx4 v184, v[188:191], s[68:69] offset:256
	global_store_dwordx2 v185, v[192:193], s[14:15] offset:128
	v_mul_f32_e32 v5, v5, v5
	v_mul_f32_e32 v7, v7, v7
	v_mul_f32_e32 v1, v1, v1
	v_mul_f32_e32 v3, v3, v3
	v_fmac_f32_e32 v5, v4, v4
	v_fmac_f32_e32 v7, v6, v6
	v_fmac_f32_e32 v1, v0, v0
	v_fmac_f32_e32 v3, v2, v2
	v_add_f32_e32 v5, v5, v7
	v_add_f32_e32 v5, v5, v1
	v_add_f32_e32 v5, v3, v5
	v_add_f32_e32 v249, v249, v5
	ds_bpermute_b32 v188, v254, v194
	ds_bpermute_b32 v189, v254, v195
	ds_bpermute_b32 v190, v254, v196
	ds_bpermute_b32 v191, v254, v249
	s_waitcnt lgkmcnt(0)
	v_add_f32_e32 v194, v194, v188
	v_add_f32_e32 v195, v195, v189
	v_add_f32_e32 v196, v196, v190
	v_add_f32_e32 v249, v249, v191
	ds_bpermute_b32 v188, v255, v194
	ds_bpermute_b32 v189, v255, v195
	ds_bpermute_b32 v190, v255, v196
	ds_bpermute_b32 v191, v255, v249
	s_waitcnt lgkmcnt(0)
	v_add_f32_e32 v194, v194, v188
	v_add_f32_e32 v195, v195, v189
	v_add_f32_e32 v196, v196, v190
	v_add_f32_e32 v249, v249, v191
	s_and_saveexec_b64 s[28:29], s[4:5]
	global_atomic_add_f32 v253, v194, s[12:13] offset:512
	global_atomic_add_f32 v253, v195, s[12:13] offset:576
	global_atomic_add_f32 v253, v196, s[12:13] offset:640
	global_atomic_add_f32 v253, v249, s[12:13] offset:704
	s_or_b64 exec, exec, s[28:29]
	s_andn2_b64 vcc, exec, s[6:7]
	s_mov_b64 s[6:7], -1
	s_cbranch_vccnz .LBB0_858
	s_andn2_b64 vcc, exec, s[10:11]
	s_cbranch_vccnz .LBB0_857
	s_barrier
	s_branch .LBB0_857

.LpgL1_group:
	v_mbcnt_lo_u32_b32 v249, -1, 0
	v_mbcnt_hi_u32_b32 v249, -1, v249
	v_and_b32_e32 v250, 15, v249
	v_lshrrev_b32_e32 v251, 4, v249
	v_and_b32_e32 v252, 3, v250
	v_cmp_eq_u32_e64 s[4:5], 1, v252
	v_cmp_eq_u32_e64 s[6:7], 2, v252
	v_cmp_eq_u32_e64 s[8:9], 3, v252
	v_cmp_eq_u32_e64 s[10:11], 0, v249
	s_add_u32 s12, s54, 0x29800000
	s_addc_u32 s13, s55, 0
	s_and_b32 s13, s13, 0xffff
	s_mov_b32 s14, 0x2000000
	s_mov_b32 s15, 0x20000
	s_add_u32 s16, s54, 0x10000000
	s_addc_u32 s17, s55, 0
	s_and_b32 s17, s17, 0xffff
	s_mov_b32 s18, 0x1000000
	s_mov_b32 s19, 0x20000
	s_add_u32 s20, s54, 0x14000000
	s_addc_u32 s21, s55, 0
	s_and_b32 s21, s21, 0xffff
	s_mov_b32 s22, 0x1000000
	s_mov_b32 s23, 0x20000
	s_add_u32 s30, s54, 0xa0000
	s_addc_u32 s31, s55, 0
	s_add_u32 s34, s54, 0xe0000
	s_addc_u32 s35, s55, 0
	s_mov_b32 s94, 0xc3e00000
	s_mov_b32 s96, 0x800000
	s_mov_b32 s81, 0x1010101
	v_lshrrev_b32_e32 v253, 2, v250
	v_lshrrev_b32_e32 v254, 1, v251
	v_lshl_add_u32 v255, v253, 1, v254
	v_lshl_add_u32 v237, v255, 2, s91
	v_and_b32_e32 v255, 1, v251
	v_lshl_add_u32 v236, v255, 2, v252
	v_lshlrev_b32_e32 v236, 4, v236
	v_lshlrev_b32_e32 v254, 7, v254
	v_lshl_add_u32 v254, v252, 5, v254
	v_lshl_add_u32 v254, v255, 4, v254
	v_and_b32_e32 v253, 1, v253
	v_mov_b32_e32 v255, 0x7fff0000
	v_cmp_eq_u32_e32 vcc, 0, v253
	s_nop 1
	v_cndmask_b32_e32 v238, v255, v254, vcc
	v_cndmask_b32_e32 v239, v254, v255, vcc
	v_mov_b32_e32 v240, 0x7f7f7f7f
	v_mov_b32_e32 v255, 0x20202020
	v_cmp_gt_u32_e32 vcc, 8, v250
	s_nop 1
	v_cndmask_b32_e32 v241, v255, v240, vcc
	v_cndmask_b32_e32 v242, v240, v255, vcc
	v_lshrrev_b32_e32 v254, 3, v250
	v_lshl_add_u32 v254, v252, 1, v254
	v_lshl_add_u32 v255, v251, 1, v253
	v_lshl_add_u32 v244, v254, 3, v255
	v_lshlrev_b32_e32 v244, 2, v244
	v_add_u32_e32 v243, s91, v244
	v_and_b32_e32 v253, 3, v255
	v_lshrrev_b32_e32 v255, 2, v255
	v_lshl_add_u32 v253, v253, 1, v255
	v_lshl_add_u32 v253, v254, 3, v253
	v_lshlrev_b32_e32 v253, 2, v253
	v_add_u32_e32 v245, s91, v253
	v_add_u32_e32 v245, 0x1000, v245
	v_mov_b32_e32 v246, 0
	s_lshl_b32 s64, s63, 12
	s_add_u32 s24, s54, 0x28000000
	s_addc_u32 s25, s55, 0
	s_add_u32 s24, s24, s64
	s_addc_u32 s25, s25, 0
	s_lshl_b32 s64, s63, 12
	s_add_u32 s26, s54, 0x28800000
	s_addc_u32 s27, s55, 0
	s_add_u32 s26, s26, s64
	s_addc_u32 s27, s27, 0
	s_lshl_b32 s64, s63, 15
	s_add_u32 s28, s54, 0x18000000
	s_addc_u32 s29, s55, 0
	s_add_u32 s28, s28, s64
	s_addc_u32 s29, s29, 0
	s_lshl_b32 s64, s63, 5
	s_add_u32 s40, s54, 0x60000
	s_addc_u32 s41, s55, 0
	s_add_u32 s40, s40, s64
	s_addc_u32 s41, s41, 0
	s_lshl_b32 s64, s63, 5
	s_add_u32 s44, s54, 0x70000
	s_addc_u32 s45, s55, 0
	s_add_u32 s44, s44, s64
	s_addc_u32 s45, s45, 0
	s_lshl_b32 s64, s63, 16
	s_mov_b32 s46, s52
	s_mov_b32 s47, s53
	s_add_u32 s46, s46, s64
	s_addc_u32 s47, s47, 0
	s_lshl_b32 s61, s63, 14
	s_add_u32 s62, s61, 0x100
	v_mbcnt_lo_u32_b32 v253, -1, 0
	v_mbcnt_hi_u32_b32 v253, -1, v253
	v_lshlrev_b32_e32 v253, 2, v253
	global_load_dword v0, v253, s[24:25] offset:0
	global_load_dword v1, v253, s[24:25] offset:256
	global_load_dword v2, v253, s[24:25] offset:512
	global_load_dword v3, v253, s[24:25] offset:768
	global_load_dword v4, v253, s[24:25] offset:1024
	global_load_dword v5, v253, s[24:25] offset:1280
	global_load_dword v6, v253, s[24:25] offset:1536
	global_load_dword v7, v253, s[24:25] offset:1792
	global_load_dword v8, v253, s[24:25] offset:2048
	global_load_dword v9, v253, s[24:25] offset:2304
	global_load_dword v10, v253, s[24:25] offset:2560
	global_load_dword v11, v253, s[24:25] offset:2816
	global_load_dword v12, v253, s[24:25] offset:3072
	global_load_dword v13, v253, s[24:25] offset:3328
	global_load_dword v14, v253, s[24:25] offset:3584
	global_load_dword v15, v253, s[24:25] offset:3840
	v_add_u32_e32 v254, s91, v253
	s_waitcnt vmcnt(0)
	ds_write_b32 v254, v0 offset:0
	ds_write_b32 v254, v1 offset:256
	ds_write_b32 v254, v2 offset:512
	ds_write_b32 v254, v3 offset:768
	ds_write_b32 v254, v4 offset:1024
	ds_write_b32 v254, v5 offset:1280
	ds_write_b32 v254, v6 offset:1536
	ds_write_b32 v254, v7 offset:1792
	ds_write_b32 v254, v8 offset:2048
	ds_write_b32 v254, v9 offset:2304
	ds_write_b32 v254, v10 offset:2560
	ds_write_b32 v254, v11 offset:2816
	ds_write_b32 v254, v12 offset:3072
	ds_write_b32 v254, v13 offset:3328
	ds_write_b32 v254, v14 offset:3584
	ds_write_b32 v254, v15 offset:3840
	s_waitcnt lgkmcnt(0)
	s_lshl_b32 s61, s63, 14
	s_add_u32 s62, s61, 0x100
	v_mov_b32_e32 v204, 0
	v_mov_b32_e32 v205, 0
	v_mov_b32_e32 v206, 0
	v_mov_b32_e32 v207, 0
	v_mov_b32_e32 v208, 0
	v_mov_b32_e32 v209, 0
	v_mov_b32_e32 v210, 0
	v_mov_b32_e32 v211, 0
	v_mov_b32_e32 v212, 0
	v_mov_b32_e32 v213, 0
	v_mov_b32_e32 v214, 0
	v_mov_b32_e32 v215, 0
	v_mov_b32_e32 v216, 0
	v_mov_b32_e32 v217, 0
	v_mov_b32_e32 v218, 0
	v_mov_b32_e32 v219, 0
	v_mov_b32_e32 v176, 0
	v_mov_b32_e32 v177, 0
	v_mov_b32_e32 v178, 0
	v_mov_b32_e32 v179, 0
	v_mov_b32_e32 v180, 0
	v_mov_b32_e32 v181, 0
	v_mov_b32_e32 v182, 0
	v_mov_b32_e32 v183, 0
	v_mov_b32_e32 v184, 0
	v_mov_b32_e32 v185, 0
	v_mov_b32_e32 v186, 0
	v_mov_b32_e32 v187, 0
	v_mov_b32_e32 v188, 0
	v_mov_b32_e32 v189, 0
	v_mov_b32_e32 v190, 0
	v_mov_b32_e32 v191, 0
	s_mov_b32 s0, 0
	s_mov_b32 s1, 0
	s_mov_b32 s60, 0x200000
	ds_read_b32 v144, v237 offset:0
	ds_read_b32 v145, v237 offset:32
	ds_read_b32 v146, v237 offset:64
	ds_read_b32 v147, v237 offset:96
	ds_read_b32 v148, v237 offset:128
	ds_read_b32 v149, v237 offset:160
	ds_read_b32 v150, v237 offset:192
	ds_read_b32 v151, v237 offset:224
	s_waitcnt lgkmcnt(0)
	v_lshl_or_b32 v144, v144, 7, v236
	v_lshl_or_b32 v145, v145, 7, v236
	v_lshl_or_b32 v146, v146, 7, v236
	v_lshl_or_b32 v147, v147, 7, v236
	v_lshl_or_b32 v148, v148, 7, v236
	v_lshl_or_b32 v149, v149, 7, v236
	v_lshl_or_b32 v150, v150, 7, v236
	v_lshl_or_b32 v151, v151, 7, v236
	buffer_load_dwordx4 v[0:3], v144, s[16:19], s1 offen
	buffer_load_dwordx4 v[4:7], v145, s[16:19], s1 offen
	buffer_load_dwordx4 v[8:11], v146, s[16:19], s1 offen
	buffer_load_dwordx4 v[12:15], v147, s[16:19], s1 offen
	buffer_load_dwordx4 v[16:19], v148, s[16:19], s1 offen
	buffer_load_dwordx4 v[20:23], v149, s[16:19], s1 offen
	buffer_load_dwordx4 v[24:27], v150, s[16:19], s1 offen
	buffer_load_dwordx4 v[28:31], v151, s[16:19], s1 offen
	ds_read_b32 v144, v237 offset:256
	ds_read_b32 v145, v237 offset:288
	ds_read_b32 v146, v237 offset:320
	ds_read_b32 v147, v237 offset:352
	ds_read_b32 v148, v237 offset:384
	ds_read_b32 v149, v237 offset:416
	ds_read_b32 v150, v237 offset:448
	ds_read_b32 v151, v237 offset:480
	s_add_u32 s80, s61, 0x0
	buffer_load_dwordx4 v[128:131], v238, s[12:15], s80 offen
	buffer_load_dwordx4 v[132:135], v239, s[12:15], s80 offen
	s_waitcnt lgkmcnt(0)
	v_lshl_or_b32 v144, v144, 7, v236
	v_lshl_or_b32 v145, v145, 7, v236
	v_lshl_or_b32 v146, v146, 7, v236
	v_lshl_or_b32 v147, v147, 7, v236
	v_lshl_or_b32 v148, v148, 7, v236
	v_lshl_or_b32 v149, v149, 7, v236
	v_lshl_or_b32 v150, v150, 7, v236
	v_lshl_or_b32 v151, v151, 7, v236
	buffer_load_dwordx4 v[32:35], v144, s[16:19], s1 offen
	buffer_load_dwordx4 v[36:39], v145, s[16:19], s1 offen
	buffer_load_dwordx4 v[40:43], v146, s[16:19], s1 offen
	buffer_load_dwordx4 v[44:47], v147, s[16:19], s1 offen
	buffer_load_dwordx4 v[48:51], v148, s[16:19], s1 offen
	buffer_load_dwordx4 v[52:55], v149, s[16:19], s1 offen
	buffer_load_dwordx4 v[56:59], v150, s[16:19], s1 offen
	buffer_load_dwordx4 v[60:63], v151, s[16:19], s1 offen
	ds_read_b32 v144, v237 offset:512
	ds_read_b32 v145, v237 offset:544
	ds_read_b32 v146, v237 offset:576
	ds_read_b32 v147, v237 offset:608
	ds_read_b32 v148, v237 offset:640
	ds_read_b32 v149, v237 offset:672
	ds_read_b32 v150, v237 offset:704
	ds_read_b32 v151, v237 offset:736
	s_waitcnt lgkmcnt(0)
	v_lshl_or_b32 v144, v144, 7, v236
	v_lshl_or_b32 v145, v145, 7, v236
	v_lshl_or_b32 v146, v146, 7, v236
	v_lshl_or_b32 v147, v147, 7, v236
	v_lshl_or_b32 v148, v148, 7, v236
	v_lshl_or_b32 v149, v149, 7, v236
	v_lshl_or_b32 v150, v150, 7, v236
	v_lshl_or_b32 v151, v151, 7, v236
	buffer_load_dwordx4 v[64:67], v144, s[16:19], s1 offen
	buffer_load_dwordx4 v[68:71], v145, s[16:19], s1 offen
	buffer_load_dwordx4 v[72:75], v146, s[16:19], s1 offen
	buffer_load_dwordx4 v[76:79], v147, s[16:19], s1 offen
	buffer_load_dwordx4 v[80:83], v148, s[16:19], s1 offen
	buffer_load_dwordx4 v[84:87], v149, s[16:19], s1 offen
	buffer_load_dwordx4 v[88:91], v150, s[16:19], s1 offen
	buffer_load_dwordx4 v[92:95], v151, s[16:19], s1 offen
	ds_read_b32 v144, v237 offset:768
	ds_read_b32 v145, v237 offset:800
	ds_read_b32 v146, v237 offset:832
	ds_read_b32 v147, v237 offset:864
	ds_read_b32 v148, v237 offset:896
	ds_read_b32 v149, v237 offset:928
	ds_read_b32 v150, v237 offset:960
	ds_read_b32 v151, v237 offset:992
